# P4 patch + loop-edge rotation: K-loop pointer/counter SALU block moved from after the last s_barrier into the last MFMA cluster (6 loops), pure reorder
# speedup vs baseline: 1.0031x; 1.0031x over previous
; #define PG8_STAGE(bufoff, gbase, voff) do { _Pragma("unroll") for (int _i = 0; _i < 2; ++_i) \
;         __builtin_amdgcn_global_load_lds((const unsigned*)((const char*)(gbase) + (voff)[_i]), (PG8_LAS unsigned*)(lds + (bufoff) + ldsw + _i * 8192), 16, 0, 0); } while (0)
; #define PG8_LDA(dst, b, h) do { _Pragma("unroll") for (int m = 0; m < 4; ++m) frag_load<F8>(dst[m], lds + PG8_SA(b, h) + aoff + m * 2048); } while (0)
; #define PG8_LDB(dst, b, h) do { _Pragma("unroll") for (int n = 0; n < 2; ++n) frag_load<F8>(dst[n], lds + PG8_SB(b, h) + boff + n * 2048); } while (0)
; #define PG8_MMA(ai, bj, At, Bt) do { __builtin_amdgcn_s_setprio(1); _Pragma("unroll") for (int m = 0; m < 4; ++m) _Pragma("unroll") for (int n = 0; n < 2; ++n) frag_mma<F8>(acc[ai][bj][m][n], Bt[n], At[m]); \
;         __builtin_amdgcn_s_setprio(0); } while (0)
; #define PG8_WAIT_V(n) asm volatile("s_waitcnt vmcnt(" #n ")" ::: "memory")
; #define PG8_WAIT_L(n) asm volatile("s_waitcnt lgkmcnt(" #n ")" ::: "memory")
; #define PG8_BAR __builtin_amdgcn_s_barrier()
; #define PG8_SCHED __builtin_amdgcn_sched_barrier(0)
; template <bool F8, class Epi, class Sched>
; __device__ __forceinline__ void gemm_phase(PG8_LAS unsigned char* lds, const Gemm g, const Sched& S, const Epi& E
;     , unsigned long long* stq = nullptr
;     ) {
;     ...
;             PG8_LDB(B0, 0, 0); PG8_LDB(B1, 0, 1); PG8_SCHED; PG8_LDA(At, 0, 0); PG8_STAGE(PG8_SA(1, 1), a1 + hstepA, voffA);
;             PG8_WAIT_V(8); PG8_WAIT_L(0); PG8_BAR; PG8_MMA(0, 0, At, B0); PG8_MMA(0, 1, At, B1); PG8_BAR; PG8_SCHED;
;             if (!hf) PG8_LDA(At, 0, 1); PG8_STAGE(PG8_SB(0, 0), b2, voffB); PG8_STAGE(PG8_SB(0, 1), b2 + hstepB, voffB); PG8_STAGE(PG8_SA(0, 0), a2, voffA);
;             PG8_WAIT_V(8); PG8_WAIT_L(0); PG8_BAR; if (!hf) { PG8_MMA(1, 0, At, B0); PG8_MMA(1, 1, At, B1); } PG8_BAR; PG8_SCHED;
.LBB0_369:
	ds_read_b128 v[4:7], v179
	ds_read_b128 v[8:11], v179 offset:1024
	ds_read_b128 v[12:15], v179 offset:2048
	ds_read_b128 v[16:19], v179 offset:3072
	ds_read_b128 v[168:171], v180
	ds_read_b128 v[186:189], v180 offset:1024
	ds_read_b128 v[190:193], v180 offset:2048
	ds_read_b128 v[194:197], v180 offset:3072
	s_add_u32 s4, s2, 0xfff80080
	s_addc_u32 s5, s3, -1
	s_cmp_eq_u32 s88, 28
	s_cselect_b32 s57, s39, s5
	s_cselect_b32 s56, s69, s4
	s_cselect_b32 s5, s21, s87
	s_cselect_b32 s4, s72, s86
	v_lshl_add_u64 v[172:173], s[2:3], 0, v[160:161]
	s_add_i32 m0, s70, 0xc000
	ds_read_b128 v[198:201], v181
	ds_read_b128 v[202:205], v181 offset:1024
	ds_read_b128 v[206:209], v181 offset:2048
	ds_read_b128 v[210:213], v181 offset:3072
	ds_read_b128 v[214:217], v181 offset:4096
	ds_read_b128 v[222:225], v181 offset:5120
	ds_read_b128 v[226:229], v181 offset:6144
	ds_read_b128 v[230:233], v181 offset:7168
	global_load_lds_dwordx4 v[172:173], off
	v_lshl_add_u64 v[172:173], s[2:3], 0, v[162:163]
	s_add_i32 m0, s70, 0xe000
	s_nop 0
	global_load_lds_dwordx4 v[172:173], off
	s_waitcnt vmcnt(8)
	s_waitcnt lgkmcnt(0)
	s_barrier
	s_setprio 1
	s_waitcnt lgkmcnt(0)
	v_mfma_f32_16x16x32_bf16 v[144:147], v[4:7], v[198:201], v[144:147]
	v_mfma_f32_16x16x32_bf16 v[140:143], v[12:15], v[198:201], v[140:143]
	v_mfma_f32_16x16x32_bf16 v[128:131], v[4:7], v[206:209], v[128:131]
	v_mfma_f32_16x16x32_bf16 v[124:127], v[12:15], v[206:209], v[124:127]
	v_mfma_f32_16x16x32_bf16 v[112:115], v[4:7], v[214:217], v[112:115]
	v_mfma_f32_16x16x32_bf16 v[108:111], v[12:15], v[214:217], v[108:111]
	v_mfma_f32_16x16x32_bf16 v[96:99], v[4:7], v[226:229], v[96:99]
	v_mfma_f32_16x16x32_bf16 v[92:95], v[12:15], v[226:229], v[92:95]
	v_mfma_f32_16x16x32_bf16 v[144:147], v[8:11], v[202:205], v[144:147]
	v_mfma_f32_16x16x32_bf16 v[140:143], v[16:19], v[202:205], v[140:143]
	v_mfma_f32_16x16x32_bf16 v[128:131], v[8:11], v[210:213], v[128:131]
	v_mfma_f32_16x16x32_bf16 v[124:127], v[16:19], v[210:213], v[124:127]
	v_mfma_f32_16x16x32_bf16 v[112:115], v[8:11], v[222:225], v[112:115]
	v_mfma_f32_16x16x32_bf16 v[108:111], v[16:19], v[222:225], v[108:111]
	v_mfma_f32_16x16x32_bf16 v[96:99], v[8:11], v[230:233], v[96:99]
	v_mfma_f32_16x16x32_bf16 v[92:95], v[16:19], v[230:233], v[92:95]
	s_setprio 0
	s_setprio 1
	v_mfma_f32_16x16x32_bf16 v[136:139], v[168:171], v[198:201], v[136:139]
	v_mfma_f32_16x16x32_bf16 v[132:135], v[190:193], v[198:201], v[132:135]
	v_mfma_f32_16x16x32_bf16 v[120:123], v[168:171], v[206:209], v[120:123]
	v_mfma_f32_16x16x32_bf16 v[116:119], v[190:193], v[206:209], v[116:119]
	v_mfma_f32_16x16x32_bf16 v[104:107], v[168:171], v[214:217], v[104:107]
	v_mfma_f32_16x16x32_bf16 v[100:103], v[190:193], v[214:217], v[100:103]
	v_mfma_f32_16x16x32_bf16 v[88:91], v[168:171], v[226:229], v[88:91]
	v_mfma_f32_16x16x32_bf16 v[84:87], v[190:193], v[226:229], v[84:87]
	v_mfma_f32_16x16x32_bf16 v[136:139], v[186:189], v[202:205], v[136:139]
	v_mfma_f32_16x16x32_bf16 v[132:135], v[194:197], v[202:205], v[132:135]
	v_mfma_f32_16x16x32_bf16 v[120:123], v[186:189], v[210:213], v[120:123]
	v_mfma_f32_16x16x32_bf16 v[116:119], v[194:197], v[210:213], v[116:119]
	v_mfma_f32_16x16x32_bf16 v[104:107], v[186:189], v[222:225], v[104:107]
	v_mfma_f32_16x16x32_bf16 v[100:103], v[194:197], v[222:225], v[100:103]
	v_mfma_f32_16x16x32_bf16 v[88:91], v[186:189], v[230:233], v[88:91]
	v_mfma_f32_16x16x32_bf16 v[84:87], v[194:197], v[230:233], v[84:87]
	s_setprio 0
	s_barrier
	s_add_i32 s10, s81, s59
	v_lshl_add_u64 v[172:173], s[4:5], 0, v[150:151]
	s_mov_b32 m0, s10
	ds_read_b128 v[198:201], v181 offset:16384
	ds_read_b128 v[202:205], v181 offset:17408
	ds_read_b128 v[206:209], v181 offset:18432
	ds_read_b128 v[210:213], v181 offset:19456
	ds_read_b128 v[214:217], v181 offset:20480
	ds_read_b128 v[222:225], v181 offset:21504
	ds_read_b128 v[226:229], v181 offset:22528
	ds_read_b128 v[230:233], v181 offset:23552
	global_load_lds_dwordx4 v[172:173], off
	s_add_i32 m0, s10, 0x2000
	s_add_u32 s90, s4, 0x80000
	v_lshl_add_u64 v[218:219], s[4:5], 0, v[154:155]
	s_addc_u32 s91, s5, 0
	s_add_i32 s10, s82, s59
	global_load_lds_dwordx4 v[218:219], off
	v_lshl_add_u64 v[234:235], s[90:91], 0, v[150:151]
	s_mov_b32 m0, s10
	v_lshl_add_u64 v[236:237], s[56:57], 0, v[152:153]
	global_load_lds_dwordx4 v[234:235], off
	v_lshl_add_u64 v[234:235], s[90:91], 0, v[154:155]
	s_add_i32 m0, s10, 0x2000
	s_nop 0
	global_load_lds_dwordx4 v[234:235], off
	v_lshl_add_u64 v[234:235], s[56:57], 0, v[148:149]
	s_mov_b32 m0, s70
	s_nop 0
	global_load_lds_dwordx4 v[234:235], off
	s_mov_b32 m0, s71
	s_nop 0
	global_load_lds_dwordx4 v[236:237], off
	s_waitcnt vmcnt(8)
	s_waitcnt lgkmcnt(0)
	s_barrier
; #define PG8_STAGE(bufoff, gbase, voff) do { _Pragma("unroll") for (int _i = 0; _i < 2; ++_i) \
;         __builtin_amdgcn_global_load_lds((const unsigned*)((const char*)(gbase) + (voff)[_i]), (PG8_LAS unsigned*)(lds + (bufoff) + ldsw + _i * 8192), 16, 0, 0); } while (0)
; #define PG8_LDA(dst, b, h) do { _Pragma("unroll") for (int m = 0; m < 4; ++m) frag_load<F8>(dst[m], lds + PG8_SA(b, h) + aoff + m * 2048); } while (0)
; #define PG8_LDB(dst, b, h) do { _Pragma("unroll") for (int n = 0; n < 2; ++n) frag_load<F8>(dst[n], lds + PG8_SB(b, h) + boff + n * 2048); } while (0)
; #define PG8_MMA(ai, bj, At, Bt) do { __builtin_amdgcn_s_setprio(1); _Pragma("unroll") for (int m = 0; m < 4; ++m) _Pragma("unroll") for (int n = 0; n < 2; ++n) frag_mma<F8>(acc[ai][bj][m][n], Bt[n], At[m]); \
;         __builtin_amdgcn_s_setprio(0); } while (0)
; #define PG8_WAIT_V(n) asm volatile("s_waitcnt vmcnt(" #n ")" ::: "memory")
; #define PG8_WAIT_L(n) asm volatile("s_waitcnt lgkmcnt(" #n ")" ::: "memory")
; #define PG8_BAR __builtin_amdgcn_s_barrier()
; #define PG8_SCHED __builtin_amdgcn_sched_barrier(0)
; template <bool F8, class Epi, class Sched>
; __device__ __forceinline__ void gemm_phase(PG8_LAS unsigned char* lds, const Gemm g, const Sched& S, const Epi& E
;     , unsigned long long* stq = nullptr
;     ) {
;     ...
;             PG8_WAIT_V(8); PG8_WAIT_L(0); PG8_BAR; if (!hf) { PG8_MMA(1, 0, At, B0); PG8_MMA(1, 1, At, B1); } PG8_BAR; PG8_SCHED;
;             PG8_LDB(B0, 1, 0); PG8_LDB(B1, 1, 1); PG8_SCHED; PG8_LDA(At, 1, 0); PG8_STAGE(PG8_SA(0, 1), a2 + hstepA, voffA);
;             PG8_WAIT_V(8); PG8_WAIT_L(0); PG8_BAR; PG8_MMA(0, 0, At, B0); PG8_MMA(0, 1, At, B1); PG8_BAR; PG8_SCHED;
	s_setprio 1
	s_waitcnt lgkmcnt(0)
	v_mfma_f32_16x16x32_bf16 v[80:83], v[4:7], v[198:201], v[80:83]
	v_mfma_f32_16x16x32_bf16 v[76:79], v[12:15], v[198:201], v[76:79]
	v_mfma_f32_16x16x32_bf16 v[64:67], v[4:7], v[206:209], v[64:67]
	v_mfma_f32_16x16x32_bf16 v[60:63], v[12:15], v[206:209], v[60:63]
	v_mfma_f32_16x16x32_bf16 v[48:51], v[4:7], v[214:217], v[48:51]
	v_mfma_f32_16x16x32_bf16 v[44:47], v[12:15], v[214:217], v[44:47]
	v_mfma_f32_16x16x32_bf16 v[4:7], v[4:7], v[226:229], v[32:35]
	v_mfma_f32_16x16x32_bf16 v[80:83], v[8:11], v[202:205], v[80:83]
	v_mfma_f32_16x16x32_bf16 v[76:79], v[16:19], v[202:205], v[76:79]
	v_mfma_f32_16x16x32_bf16 v[64:67], v[8:11], v[210:213], v[64:67]
	v_mfma_f32_16x16x32_bf16 v[60:63], v[16:19], v[210:213], v[60:63]
	v_mfma_f32_16x16x32_bf16 v[48:51], v[8:11], v[222:225], v[48:51]
	v_mfma_f32_16x16x32_bf16 v[44:47], v[16:19], v[222:225], v[44:47]
	v_mfma_f32_16x16x32_bf16 v[4:7], v[8:11], v[230:233], v[4:7]
	v_mfma_f32_16x16x32_bf16 v[8:11], v[12:15], v[226:229], v[28:31]
	v_mfma_f32_16x16x32_bf16 v[8:11], v[16:19], v[230:233], v[8:11]
	s_setprio 0
	s_setprio 1
	v_mfma_f32_16x16x32_bf16 v[28:31], v[168:171], v[206:209], v[56:59]
	v_mfma_f32_16x16x32_bf16 v[56:59], v[186:189], v[210:213], v[28:31]
	v_mfma_f32_16x16x32_bf16 v[28:31], v[190:193], v[206:209], v[52:55]
	v_mfma_f32_16x16x32_bf16 v[52:55], v[194:197], v[210:213], v[28:31]
	v_mfma_f32_16x16x32_bf16 v[28:31], v[168:171], v[214:217], v[40:43]
	v_mfma_f32_16x16x32_bf16 v[40:43], v[186:189], v[222:225], v[28:31]
	v_mfma_f32_16x16x32_bf16 v[28:31], v[190:193], v[214:217], v[36:39]
	v_mfma_f32_16x16x32_bf16 v[24:27], v[168:171], v[226:229], v[24:27]
	v_mfma_f32_16x16x32_bf16 v[20:23], v[190:193], v[226:229], v[20:23]
	v_mfma_f32_16x16x32_bf16 v[12:15], v[168:171], v[198:201], v[72:75]
	v_mfma_f32_16x16x32_bf16 v[16:19], v[190:193], v[198:201], v[68:71]
	v_mfma_f32_16x16x32_bf16 v[36:39], v[194:197], v[222:225], v[28:31]
	v_mfma_f32_16x16x32_bf16 v[24:27], v[186:189], v[230:233], v[24:27]
	v_mfma_f32_16x16x32_bf16 v[20:23], v[194:197], v[230:233], v[20:23]
	v_mfma_f32_16x16x32_bf16 v[12:15], v[186:189], v[202:205], v[12:15]
	v_mfma_f32_16x16x32_bf16 v[16:19], v[194:197], v[202:205], v[16:19]
	s_setprio 0
	s_barrier
	s_add_i32 s10, 0, 0x18000
	v_add_u32_e32 v2, s10, v175
	s_add_i32 s52, 0, 0x1c000
	ds_read_b128 v[28:31], v2
	ds_read_b128 v[32:35], v2 offset:1024
	ds_read_b128 v[68:71], v2 offset:2048
	ds_read_b128 v[72:75], v2 offset:3072
	v_add_u32_e32 v2, s52, v175
	ds_read_b128 v[168:171], v2
	ds_read_b128 v[186:189], v2 offset:1024
	ds_read_b128 v[190:193], v2 offset:2048
	ds_read_b128 v[194:197], v2 offset:3072
	s_add_u32 s56, s56, 0x80000
	s_addc_u32 s57, s57, 0
	s_mov_b32 m0, s73
	v_lshl_add_u64 v[238:239], s[56:57], 0, v[148:149]
	ds_read_b128 v[198:201], v181 offset:32768
	ds_read_b128 v[202:205], v181 offset:33792
	ds_read_b128 v[206:209], v181 offset:34816
	ds_read_b128 v[210:213], v181 offset:35840
	ds_read_b128 v[214:217], v181 offset:36864
	ds_read_b128 v[222:225], v181 offset:37888
	ds_read_b128 v[226:229], v181 offset:38912
	ds_read_b128 v[230:233], v181 offset:39936
	global_load_lds_dwordx4 v[238:239], off
	v_lshl_add_u64 v[238:239], s[56:57], 0, v[152:153]
	s_mov_b32 m0, s74
	s_nop 0
	global_load_lds_dwordx4 v[238:239], off
	s_waitcnt vmcnt(8)
	s_waitcnt lgkmcnt(0)
	s_barrier
	s_setprio 1
	s_waitcnt lgkmcnt(0)
	v_mfma_f32_16x16x32_bf16 v[144:147], v[28:31], v[198:201], v[144:147]
	v_mfma_f32_16x16x32_bf16 v[140:143], v[68:71], v[198:201], v[140:143]
	v_mfma_f32_16x16x32_bf16 v[128:131], v[28:31], v[206:209], v[128:131]
	v_mfma_f32_16x16x32_bf16 v[124:127], v[68:71], v[206:209], v[124:127]
	v_mfma_f32_16x16x32_bf16 v[112:115], v[28:31], v[214:217], v[112:115]
	v_mfma_f32_16x16x32_bf16 v[108:111], v[68:71], v[214:217], v[108:111]
	v_mfma_f32_16x16x32_bf16 v[96:99], v[28:31], v[226:229], v[96:99]
	v_mfma_f32_16x16x32_bf16 v[92:95], v[68:71], v[226:229], v[92:95]
	v_mfma_f32_16x16x32_bf16 v[144:147], v[32:35], v[202:205], v[144:147]
	v_mfma_f32_16x16x32_bf16 v[140:143], v[72:75], v[202:205], v[140:143]
	v_mfma_f32_16x16x32_bf16 v[128:131], v[32:35], v[210:213], v[128:131]
	v_mfma_f32_16x16x32_bf16 v[124:127], v[72:75], v[210:213], v[124:127]
	v_mfma_f32_16x16x32_bf16 v[112:115], v[32:35], v[222:225], v[112:115]
	v_mfma_f32_16x16x32_bf16 v[108:111], v[72:75], v[222:225], v[108:111]
	v_mfma_f32_16x16x32_bf16 v[96:99], v[32:35], v[230:233], v[96:99]
	v_mfma_f32_16x16x32_bf16 v[92:95], v[72:75], v[230:233], v[92:95]
	s_setprio 0
	s_setprio 1
	v_mfma_f32_16x16x32_bf16 v[136:139], v[168:171], v[198:201], v[136:139]
	v_mfma_f32_16x16x32_bf16 v[132:135], v[190:193], v[198:201], v[132:135]
	v_mfma_f32_16x16x32_bf16 v[120:123], v[168:171], v[206:209], v[120:123]
	v_mfma_f32_16x16x32_bf16 v[116:119], v[190:193], v[206:209], v[116:119]
	v_mfma_f32_16x16x32_bf16 v[104:107], v[168:171], v[214:217], v[104:107]
	v_mfma_f32_16x16x32_bf16 v[100:103], v[190:193], v[214:217], v[100:103]
	v_mfma_f32_16x16x32_bf16 v[88:91], v[168:171], v[226:229], v[88:91]
	v_mfma_f32_16x16x32_bf16 v[84:87], v[190:193], v[226:229], v[84:87]
	v_mfma_f32_16x16x32_bf16 v[136:139], v[186:189], v[202:205], v[136:139]
	v_mfma_f32_16x16x32_bf16 v[132:135], v[194:197], v[202:205], v[132:135]
	v_mfma_f32_16x16x32_bf16 v[120:123], v[186:189], v[210:213], v[120:123]
	v_mfma_f32_16x16x32_bf16 v[116:119], v[194:197], v[210:213], v[116:119]
	v_mfma_f32_16x16x32_bf16 v[104:107], v[186:189], v[222:225], v[104:107]
	v_mfma_f32_16x16x32_bf16 v[100:103], v[194:197], v[222:225], v[100:103]
	v_mfma_f32_16x16x32_bf16 v[88:91], v[186:189], v[230:233], v[88:91]
	v_mfma_f32_16x16x32_bf16 v[84:87], v[194:197], v[230:233], v[84:87]
	s_setprio 0
	s_barrier
; #define PG8_STAGE(bufoff, gbase, voff) do { _Pragma("unroll") for (int _i = 0; _i < 2; ++_i) \
;         __builtin_amdgcn_global_load_lds((const unsigned*)((const char*)(gbase) + (voff)[_i]), (PG8_LAS unsigned*)(lds + (bufoff) + ldsw + _i * 8192), 16, 0, 0); } while (0)
; #define PG8_LDA(dst, b, h) do { _Pragma("unroll") for (int m = 0; m < 4; ++m) frag_load<F8>(dst[m], lds + PG8_SA(b, h) + aoff + m * 2048); } while (0)
; #define PG8_MMA(ai, bj, At, Bt) do { __builtin_amdgcn_s_setprio(1); _Pragma("unroll") for (int m = 0; m < 4; ++m) _Pragma("unroll") for (int n = 0; n < 2; ++n) frag_mma<F8>(acc[ai][bj][m][n], Bt[n], At[m]); \
;         __builtin_amdgcn_s_setprio(0); } while (0)
; #define PG8_WAIT_V(n) asm volatile("s_waitcnt vmcnt(" #n ")" ::: "memory")
; #define PG8_WAIT_L(n) asm volatile("s_waitcnt lgkmcnt(" #n ")" ::: "memory")
; #define PG8_BAR __builtin_amdgcn_s_barrier()
; #define PG8_SCHED __builtin_amdgcn_sched_barrier(0)
; template <bool F8, class Epi, class Sched>
; __device__ __forceinline__ void gemm_phase(PG8_LAS unsigned char* lds, const Gemm g, const Sched& S, const Epi& E
;     , unsigned long long* stq = nullptr
;     ) {
;     ...
;             if (!hf) PG8_LDA(At, 1, 1); PG8_STAGE(PG8_SB(1, 0), b3, voffB); PG8_STAGE(PG8_SB(1, 1), b3 + hstepB, voffB); PG8_STAGE(PG8_SA(1, 0), a3, voffA);
;             PG8_WAIT_V(8); PG8_WAIT_L(0); PG8_BAR; if (!hf) { PG8_MMA(1, 0, At, B0); PG8_MMA(1, 1, At, B1); } PG8_BAR; PG8_SCHED;
;         }
	s_add_i32 s10, s10, s59
	v_lshl_add_u64 v[172:173], v[172:173], 0, s[14:15]
	s_mov_b32 m0, s10
	ds_read_b128 v[198:201], v181 offset:49152
	ds_read_b128 v[202:205], v181 offset:50176
	ds_read_b128 v[206:209], v181 offset:51200
	ds_read_b128 v[210:213], v181 offset:52224
	ds_read_b128 v[214:217], v181 offset:53248
	ds_read_b128 v[222:225], v181 offset:54272
	ds_read_b128 v[226:229], v181 offset:55296
	ds_read_b128 v[230:233], v181 offset:56320
	global_load_lds_dwordx4 v[172:173], off
	s_add_i32 m0, s10, 0x2000
	s_add_u32 s4, s4, 0x80080
	v_lshl_add_u64 v[172:173], v[218:219], 0, s[14:15]
	s_addc_u32 s5, s5, 0
	s_add_i32 s10, s52, s59
	global_load_lds_dwordx4 v[172:173], off
	v_lshl_add_u64 v[172:173], s[4:5], 0, v[150:151]
	s_mov_b32 m0, s10
	s_nop 0
	global_load_lds_dwordx4 v[172:173], off
	v_lshl_add_u64 v[172:173], s[4:5], 0, v[154:155]
	s_add_i32 m0, s10, 0x2000
	s_nop 0
	global_load_lds_dwordx4 v[172:173], off
	v_lshl_add_u64 v[172:173], v[234:235], 0, s[14:15]
	s_mov_b32 m0, s77
	s_nop 0
	global_load_lds_dwordx4 v[172:173], off
	v_lshl_add_u64 v[172:173], v[236:237], 0, s[14:15]
	s_mov_b32 m0, s78
	s_nop 0
	global_load_lds_dwordx4 v[172:173], off
	s_waitcnt vmcnt(8)
	s_waitcnt lgkmcnt(0)
	s_barrier
	s_setprio 1
	s_waitcnt lgkmcnt(0)
	v_mfma_f32_16x16x32_bf16 v[80:83], v[28:31], v[198:201], v[80:83]
	v_mfma_f32_16x16x32_bf16 v[64:67], v[28:31], v[206:209], v[64:67]
	v_mfma_f32_16x16x32_bf16 v[48:51], v[28:31], v[214:217], v[48:51]
	v_mfma_f32_16x16x32_bf16 v[4:7], v[28:31], v[226:229], v[4:7]
	v_mfma_f32_16x16x32_bf16 v[80:83], v[32:35], v[202:205], v[80:83]
	v_mfma_f32_16x16x32_bf16 v[76:79], v[68:71], v[198:201], v[76:79]
	v_mfma_f32_16x16x32_bf16 v[64:67], v[32:35], v[210:213], v[64:67]
	v_mfma_f32_16x16x32_bf16 v[60:63], v[68:71], v[206:209], v[60:63]
	v_mfma_f32_16x16x32_bf16 v[48:51], v[32:35], v[222:225], v[48:51]
	v_mfma_f32_16x16x32_bf16 v[44:47], v[68:71], v[214:217], v[44:47]
	v_mfma_f32_16x16x32_bf16 v[32:35], v[32:35], v[230:233], v[4:7]
	v_mfma_f32_16x16x32_bf16 v[4:7], v[68:71], v[226:229], v[8:11]
	v_mfma_f32_16x16x32_bf16 v[76:79], v[72:75], v[202:205], v[76:79]
	v_mfma_f32_16x16x32_bf16 v[60:63], v[72:75], v[210:213], v[60:63]
	v_mfma_f32_16x16x32_bf16 v[44:47], v[72:75], v[222:225], v[44:47]
	v_mfma_f32_16x16x32_bf16 v[28:31], v[72:75], v[230:233], v[4:7]
	s_setprio 0
	s_setprio 1
	v_mfma_f32_16x16x32_bf16 v[4:7], v[168:171], v[198:201], v[12:15]
	s_add_i32 s88, s88, 2
	v_mfma_f32_16x16x32_bf16 v[72:75], v[186:189], v[202:205], v[4:7]
	s_add_u32 s2, s2, 0x100
	v_mfma_f32_16x16x32_bf16 v[4:7], v[190:193], v[198:201], v[16:19]
	s_addc_u32 s3, s3, 0
	v_mfma_f32_16x16x32_bf16 v[68:71], v[194:197], v[202:205], v[4:7]
	s_add_u32 s86, s86, 0x100
	v_mfma_f32_16x16x32_bf16 v[4:7], v[168:171], v[206:209], v[56:59]
	s_addc_u32 s87, s87, 0
	v_mfma_f32_16x16x32_bf16 v[56:59], v[186:189], v[210:213], v[4:7]
	s_cmp_gt_u32 s88, 29
	v_mfma_f32_16x16x32_bf16 v[4:7], v[190:193], v[206:209], v[52:55]
	v_mfma_f32_16x16x32_bf16 v[52:55], v[194:197], v[210:213], v[4:7]
	v_mfma_f32_16x16x32_bf16 v[4:7], v[168:171], v[214:217], v[40:43]
	v_mfma_f32_16x16x32_bf16 v[40:43], v[186:189], v[222:225], v[4:7]
	v_mfma_f32_16x16x32_bf16 v[4:7], v[190:193], v[214:217], v[36:39]
	v_mfma_f32_16x16x32_bf16 v[36:39], v[194:197], v[222:225], v[4:7]
	v_mfma_f32_16x16x32_bf16 v[4:7], v[168:171], v[226:229], v[24:27]
	v_mfma_f32_16x16x32_bf16 v[24:27], v[186:189], v[230:233], v[4:7]
	v_mfma_f32_16x16x32_bf16 v[4:7], v[190:193], v[226:229], v[20:23]
	v_mfma_f32_16x16x32_bf16 v[20:23], v[194:197], v[230:233], v[4:7]
	s_setprio 0
	s_barrier
	s_cbranch_scc0 .LBB0_369
	s_and_b64 vcc, exec, s[16:17]
	s_cbranch_vccz .LBB0_372
	s_barrier

; #define PG8_STAGE(bufoff, gbase, voff) do { _Pragma("unroll") for (int _i = 0; _i < 2; ++_i) \
;         __builtin_amdgcn_global_load_lds((const unsigned*)((const char*)(gbase) + (voff)[_i]), (PG8_LAS unsigned*)(lds + (bufoff) + ldsw + _i * 8192), 16, 0, 0); } while (0)
; #define PG8_LDA(dst, b, h) do { _Pragma("unroll") for (int m = 0; m < 4; ++m) frag_load<F8>(dst[m], lds + PG8_SA(b, h) + aoff + m * 2048); } while (0)
; #define PG8_LDB(dst, b, h) do { _Pragma("unroll") for (int n = 0; n < 2; ++n) frag_load<F8>(dst[n], lds + PG8_SB(b, h) + boff + n * 2048); } while (0)
; #define PG8_MMA(ai, bj, At, Bt) do { __builtin_amdgcn_s_setprio(1); _Pragma("unroll") for (int m = 0; m < 4; ++m) _Pragma("unroll") for (int n = 0; n < 2; ++n) frag_mma<F8>(acc[ai][bj][m][n], Bt[n], At[m]); \
;         __builtin_amdgcn_s_setprio(0); } while (0)
; #define PG8_WAIT_V(n) asm volatile("s_waitcnt vmcnt(" #n ")" ::: "memory")
; #define PG8_WAIT_L(n) asm volatile("s_waitcnt lgkmcnt(" #n ")" ::: "memory")
; #define PG8_BAR __builtin_amdgcn_s_barrier()
; #define PG8_SCHED __builtin_amdgcn_sched_barrier(0)
; template <bool F8, class Epi, class Sched>
; __device__ __forceinline__ void gemm_phase(PG8_LAS unsigned char* lds, const Gemm g, const Sched& S, const Epi& E
;     , unsigned long long* stq = nullptr
;     ) {
;     ...
;             const char* a1 = cA + (size_t)(t + 1) * kstep;
;             const char* a2 = last ? nA : cA + (size_t)(t + 2) * kstep; const char* b2 = last ? nB : cB + (size_t)(t + 2) * kstep;
;             const char* a3 = a2 + kstep; const char* b3 = b2 + kstep;
;             PG8_LDB(B0, 0, 0); PG8_LDB(B1, 0, 1); PG8_SCHED; PG8_LDA(At, 0, 0); PG8_STAGE(PG8_SA(1, 1), a1 + hstepA, voffA);
;             PG8_WAIT_V(8); PG8_WAIT_L(0); PG8_BAR; PG8_MMA(0, 0, At, B0); PG8_MMA(0, 1, At, B1); PG8_BAR; PG8_SCHED;
;             if (!hf) PG8_LDA(At, 0, 1); PG8_STAGE(PG8_SB(0, 0), b2, voffB); PG8_STAGE(PG8_SB(0, 1), b2 + hstepB, voffB); PG8_STAGE(PG8_SA(0, 0), a2, voffA);
;             PG8_WAIT_V(8); PG8_WAIT_L(0); PG8_BAR; if (!hf) { PG8_MMA(1, 0, At, B0); PG8_MMA(1, 1, At, B1); } PG8_BAR; PG8_SCHED;
.LBB0_804:
	ds_read_b128 v[18:21], v184
	ds_read_b128 v[22:25], v184 offset:1024
	ds_read_b128 v[26:29], v184 offset:2048
	ds_read_b128 v[30:33], v184 offset:3072
	ds_read_b128 v[2:5], v185
	ds_read_b128 v[6:9], v185 offset:1024
	ds_read_b128 v[10:13], v185 offset:2048
	ds_read_b128 v[14:17], v185 offset:3072
	s_add_i32 s10, s76, 2
	s_add_u32 s52, s60, 0xfff80080
	s_addc_u32 s53, s61, -1
	s_cmp_eq_u32 s97, s76
	s_cselect_b32 s76, s96, vcc_lo
	s_cselect_b32 s79, s94, s53
	s_cselect_b32 s78, s95, s52
	s_cselect_b32 s77, s39, vcc_hi
	v_lshl_add_u64 v[212:213], s[60:61], 0, v[170:171]
	s_add_i32 m0, s73, 0xc000
	ds_read_b128 v[174:177], v186
	ds_read_b128 v[178:181], v186 offset:1024
	ds_read_b128 v[188:191], v186 offset:2048
	ds_read_b128 v[192:195], v186 offset:3072
	ds_read_b128 v[196:199], v186 offset:4096
	ds_read_b128 v[200:203], v186 offset:5120
	ds_read_b128 v[204:207], v186 offset:6144
	ds_read_b128 v[208:211], v186 offset:7168
	global_load_lds_dwordx4 v[212:213], off
	v_lshl_add_u64 v[212:213], s[60:61], 0, v[172:173]
	s_add_i32 m0, s73, 0xe000
	s_nop 0
	global_load_lds_dwordx4 v[212:213], off
	s_waitcnt vmcnt(8)
	s_waitcnt lgkmcnt(0)
	s_barrier
	s_setprio 1
	s_waitcnt lgkmcnt(0)
	v_mfma_scale_f32_16x16x128_f8f6f4 v[158:161], v[18:25], v[174:181], v[158:161], v187, v187 op_sel_hi:[0,0,0]
	v_mfma_scale_f32_16x16x128_f8f6f4 v[154:157], v[26:33], v[174:181], v[154:157], v187, v187 op_sel_hi:[0,0,0]
	v_mfma_scale_f32_16x16x128_f8f6f4 v[146:149], v[18:25], v[188:195], v[146:149], v187, v187 op_sel_hi:[0,0,0]
	v_mfma_scale_f32_16x16x128_f8f6f4 v[138:141], v[26:33], v[188:195], v[138:141], v187, v187 op_sel_hi:[0,0,0]
	v_mfma_scale_f32_16x16x128_f8f6f4 v[130:133], v[18:25], v[196:203], v[130:133], v187, v187 op_sel_hi:[0,0,0]
	v_mfma_scale_f32_16x16x128_f8f6f4 v[122:125], v[26:33], v[196:203], v[122:125], v187, v187 op_sel_hi:[0,0,0]
	v_mfma_scale_f32_16x16x128_f8f6f4 v[114:117], v[18:25], v[204:211], v[114:117], v187, v187 op_sel_hi:[0,0,0]
	v_mfma_scale_f32_16x16x128_f8f6f4 v[106:109], v[26:33], v[204:211], v[106:109], v187, v187 op_sel_hi:[0,0,0]
	s_setprio 0
	s_setprio 1
	v_mfma_scale_f32_16x16x128_f8f6f4 v[150:153], v[2:9], v[174:181], v[150:153], v187, v187 op_sel_hi:[0,0,0]
	v_mfma_scale_f32_16x16x128_f8f6f4 v[142:145], v[10:17], v[174:181], v[142:145], v187, v187 op_sel_hi:[0,0,0]
	v_mfma_scale_f32_16x16x128_f8f6f4 v[134:137], v[2:9], v[188:195], v[134:137], v187, v187 op_sel_hi:[0,0,0]
	v_mfma_scale_f32_16x16x128_f8f6f4 v[126:129], v[10:17], v[188:195], v[126:129], v187, v187 op_sel_hi:[0,0,0]
	v_mfma_scale_f32_16x16x128_f8f6f4 v[118:121], v[2:9], v[196:203], v[118:121], v187, v187 op_sel_hi:[0,0,0]
	v_mfma_scale_f32_16x16x128_f8f6f4 v[110:113], v[10:17], v[196:203], v[110:113], v187, v187 op_sel_hi:[0,0,0]
	v_mfma_scale_f32_16x16x128_f8f6f4 v[102:105], v[2:9], v[204:211], v[102:105], v187, v187 op_sel_hi:[0,0,0]
	v_mfma_scale_f32_16x16x128_f8f6f4 v[98:101], v[10:17], v[204:211], v[98:101], v187, v187 op_sel_hi:[0,0,0]
	s_setprio 0
	s_barrier
	s_add_i32 s52, s85, s71
	v_lshl_add_u64 v[174:175], s[76:77], 0, v[164:165]
	s_mov_b32 m0, s52
	ds_read_b128 v[188:191], v186 offset:16384
	ds_read_b128 v[192:195], v186 offset:17408
	ds_read_b128 v[196:199], v186 offset:18432
	ds_read_b128 v[200:203], v186 offset:19456
	ds_read_b128 v[204:207], v186 offset:20480
	ds_read_b128 v[208:211], v186 offset:21504
	ds_read_b128 v[212:215], v186 offset:22528
	ds_read_b128 v[216:219], v186 offset:23552
	global_load_lds_dwordx4 v[174:175], off
	s_add_i32 m0, s52, 0x2000
	s_add_u32 s52, s76, 0x80000
	v_lshl_add_u64 v[176:177], s[76:77], 0, v[168:169]
	s_addc_u32 s53, s77, 0
	s_add_i32 s54, s86, s71
	global_load_lds_dwordx4 v[176:177], off
	v_lshl_add_u64 v[178:179], s[52:53], 0, v[164:165]
	s_mov_b32 m0, s54
	v_lshl_add_u64 v[180:181], s[78:79], 0, v[166:167]
	global_load_lds_dwordx4 v[178:179], off
	v_lshl_add_u64 v[178:179], s[52:53], 0, v[168:169]
	s_add_i32 m0, s54, 0x2000
	s_nop 0
	global_load_lds_dwordx4 v[178:179], off
	v_lshl_add_u64 v[178:179], s[78:79], 0, v[162:163]
	s_mov_b32 m0, s73
	s_nop 0
	global_load_lds_dwordx4 v[178:179], off
	s_mov_b32 m0, s74
	s_nop 0
	global_load_lds_dwordx4 v[180:181], off
	s_waitcnt vmcnt(8)
	s_waitcnt lgkmcnt(0)
	s_barrier
	s_setprio 1
	s_waitcnt lgkmcnt(0)
	v_mfma_scale_f32_16x16x128_f8f6f4 v[94:97], v[18:25], v[188:195], v[94:97], v187, v187 op_sel_hi:[0,0,0]
	v_mfma_scale_f32_16x16x128_f8f6f4 v[90:93], v[26:33], v[188:195], v[90:93], v187, v187 op_sel_hi:[0,0,0]
	v_mfma_scale_f32_16x16x128_f8f6f4 v[82:85], v[18:25], v[196:203], v[82:85], v187, v187 op_sel_hi:[0,0,0]
	v_mfma_scale_f32_16x16x128_f8f6f4 v[74:77], v[26:33], v[196:203], v[74:77], v187, v187 op_sel_hi:[0,0,0]
	v_mfma_scale_f32_16x16x128_f8f6f4 v[66:69], v[18:25], v[204:211], v[66:69], v187, v187 op_sel_hi:[0,0,0]
	v_mfma_scale_f32_16x16x128_f8f6f4 v[58:61], v[26:33], v[204:211], v[58:61], v187, v187 op_sel_hi:[0,0,0]
	v_mfma_scale_f32_16x16x128_f8f6f4 v[50:53], v[18:25], v[212:219], v[50:53], v187, v187 op_sel_hi:[0,0,0]
	v_mfma_scale_f32_16x16x128_f8f6f4 v[42:45], v[26:33], v[212:219], v[42:45], v187, v187 op_sel_hi:[0,0,0]
	s_setprio 0
	s_setprio 1
	v_mfma_scale_f32_16x16x128_f8f6f4 v[86:89], v[2:9], v[188:195], v[86:89], v187, v187 op_sel_hi:[0,0,0]
	v_mfma_scale_f32_16x16x128_f8f6f4 v[78:81], v[10:17], v[188:195], v[78:81], v187, v187 op_sel_hi:[0,0,0]
	v_mfma_scale_f32_16x16x128_f8f6f4 v[70:73], v[2:9], v[196:203], v[70:73], v187, v187 op_sel_hi:[0,0,0]
	v_mfma_scale_f32_16x16x128_f8f6f4 v[62:65], v[10:17], v[196:203], v[62:65], v187, v187 op_sel_hi:[0,0,0]
	v_mfma_scale_f32_16x16x128_f8f6f4 v[54:57], v[2:9], v[204:211], v[54:57], v187, v187 op_sel_hi:[0,0,0]
	v_mfma_scale_f32_16x16x128_f8f6f4 v[46:49], v[10:17], v[204:211], v[46:49], v187, v187 op_sel_hi:[0,0,0]
	v_mfma_scale_f32_16x16x128_f8f6f4 v[38:41], v[2:9], v[212:219], v[38:41], v187, v187 op_sel_hi:[0,0,0]
	v_mfma_scale_f32_16x16x128_f8f6f4 v[34:37], v[10:17], v[212:219], v[34:37], v187, v187 op_sel_hi:[0,0,0]
	s_setprio 0
	s_barrier
; #define PG8_STAGE(bufoff, gbase, voff) do { _Pragma("unroll") for (int _i = 0; _i < 2; ++_i) \
;         __builtin_amdgcn_global_load_lds((const unsigned*)((const char*)(gbase) + (voff)[_i]), (PG8_LAS unsigned*)(lds + (bufoff) + ldsw + _i * 8192), 16, 0, 0); } while (0)
; #define PG8_LDA(dst, b, h) do { _Pragma("unroll") for (int m = 0; m < 4; ++m) frag_load<F8>(dst[m], lds + PG8_SA(b, h) + aoff + m * 2048); } while (0)
; #define PG8_LDB(dst, b, h) do { _Pragma("unroll") for (int n = 0; n < 2; ++n) frag_load<F8>(dst[n], lds + PG8_SB(b, h) + boff + n * 2048); } while (0)
; #define PG8_MMA(ai, bj, At, Bt) do { __builtin_amdgcn_s_setprio(1); _Pragma("unroll") for (int m = 0; m < 4; ++m) _Pragma("unroll") for (int n = 0; n < 2; ++n) frag_mma<F8>(acc[ai][bj][m][n], Bt[n], At[m]); \
;         __builtin_amdgcn_s_setprio(0); } while (0)
; #define PG8_WAIT_V(n) asm volatile("s_waitcnt vmcnt(" #n ")" ::: "memory")
; #define PG8_WAIT_L(n) asm volatile("s_waitcnt lgkmcnt(" #n ")" ::: "memory")
; #define PG8_BAR __builtin_amdgcn_s_barrier()
; #define PG8_SCHED __builtin_amdgcn_sched_barrier(0)
; template <bool F8, class Epi, class Sched>
; __device__ __forceinline__ void gemm_phase(PG8_LAS unsigned char* lds, const Gemm g, const Sched& S, const Epi& E
;     , unsigned long long* stq = nullptr
;     ) {
;     ...
;             PG8_LDB(B0, 1, 0); PG8_LDB(B1, 1, 1); PG8_SCHED; PG8_LDA(At, 1, 0); PG8_STAGE(PG8_SA(0, 1), a2 + hstepA, voffA);
;             PG8_WAIT_V(8); PG8_WAIT_L(0); PG8_BAR; PG8_MMA(0, 0, At, B0); PG8_MMA(0, 1, At, B1); PG8_BAR; PG8_SCHED;
;             if (!hf) PG8_LDA(At, 1, 1); PG8_STAGE(PG8_SB(1, 0), b3, voffB); PG8_STAGE(PG8_SB(1, 1), b3 + hstepB, voffB); PG8_STAGE(PG8_SA(1, 0), a3, voffA);
;             PG8_WAIT_V(8); PG8_WAIT_L(0); PG8_BAR; if (!hf) { PG8_MMA(1, 0, At, B0); PG8_MMA(1, 1, At, B1); } PG8_BAR; PG8_SCHED;
;         }
	s_add_i32 s54, 0, 0x18000
	s_add_i32 s55, 0, 0x1c000
	v_add_u32_e32 v14, s54, v182
	v_add_u32_e32 v30, s55, v182
	ds_read_b128 v[2:5], v14
	ds_read_b128 v[6:9], v14 offset:1024
	ds_read_b128 v[10:13], v14 offset:2048
	ds_read_b128 v[14:17], v14 offset:3072
	ds_read_b128 v[18:21], v30
	ds_read_b128 v[22:25], v30 offset:1024
	ds_read_b128 v[26:29], v30 offset:2048
	ds_read_b128 v[30:33], v30 offset:3072
	s_add_u32 s52, s78, 0x80000
	s_addc_u32 s53, s79, 0
	s_mov_b32 m0, s75
	v_lshl_add_u64 v[222:223], s[52:53], 0, v[162:163]
	ds_read_b128 v[188:191], v186 offset:32768
	ds_read_b128 v[192:195], v186 offset:33792
	ds_read_b128 v[196:199], v186 offset:34816
	ds_read_b128 v[200:203], v186 offset:35840
	ds_read_b128 v[204:207], v186 offset:36864
	ds_read_b128 v[208:211], v186 offset:37888
	ds_read_b128 v[212:215], v186 offset:38912
	ds_read_b128 v[216:219], v186 offset:39936
	global_load_lds_dwordx4 v[222:223], off
	v_lshl_add_u64 v[222:223], s[52:53], 0, v[166:167]
	s_mov_b32 m0, s80
	s_nop 0
	global_load_lds_dwordx4 v[222:223], off
	s_waitcnt vmcnt(8)
	s_waitcnt lgkmcnt(0)
	s_barrier
	s_setprio 1
	s_waitcnt lgkmcnt(0)
	v_mfma_scale_f32_16x16x128_f8f6f4 v[158:161], v[2:9], v[188:195], v[158:161], v187, v187 op_sel_hi:[0,0,0]
	v_mfma_scale_f32_16x16x128_f8f6f4 v[154:157], v[10:17], v[188:195], v[154:157], v187, v187 op_sel_hi:[0,0,0]
	v_mfma_scale_f32_16x16x128_f8f6f4 v[146:149], v[2:9], v[196:203], v[146:149], v187, v187 op_sel_hi:[0,0,0]
	v_mfma_scale_f32_16x16x128_f8f6f4 v[138:141], v[10:17], v[196:203], v[138:141], v187, v187 op_sel_hi:[0,0,0]
	v_mfma_scale_f32_16x16x128_f8f6f4 v[130:133], v[2:9], v[204:211], v[130:133], v187, v187 op_sel_hi:[0,0,0]
	v_mfma_scale_f32_16x16x128_f8f6f4 v[122:125], v[10:17], v[204:211], v[122:125], v187, v187 op_sel_hi:[0,0,0]
	v_mfma_scale_f32_16x16x128_f8f6f4 v[114:117], v[2:9], v[212:219], v[114:117], v187, v187 op_sel_hi:[0,0,0]
	v_mfma_scale_f32_16x16x128_f8f6f4 v[106:109], v[10:17], v[212:219], v[106:109], v187, v187 op_sel_hi:[0,0,0]
	s_setprio 0
	s_setprio 1
	v_mfma_scale_f32_16x16x128_f8f6f4 v[150:153], v[18:25], v[188:195], v[150:153], v187, v187 op_sel_hi:[0,0,0]
	v_mfma_scale_f32_16x16x128_f8f6f4 v[142:145], v[26:33], v[188:195], v[142:145], v187, v187 op_sel_hi:[0,0,0]
	v_mfma_scale_f32_16x16x128_f8f6f4 v[134:137], v[18:25], v[196:203], v[134:137], v187, v187 op_sel_hi:[0,0,0]
	v_mfma_scale_f32_16x16x128_f8f6f4 v[126:129], v[26:33], v[196:203], v[126:129], v187, v187 op_sel_hi:[0,0,0]
	v_mfma_scale_f32_16x16x128_f8f6f4 v[118:121], v[18:25], v[204:211], v[118:121], v187, v187 op_sel_hi:[0,0,0]
	v_mfma_scale_f32_16x16x128_f8f6f4 v[110:113], v[26:33], v[204:211], v[110:113], v187, v187 op_sel_hi:[0,0,0]
	v_mfma_scale_f32_16x16x128_f8f6f4 v[102:105], v[18:25], v[212:219], v[102:105], v187, v187 op_sel_hi:[0,0,0]
	v_mfma_scale_f32_16x16x128_f8f6f4 v[98:101], v[26:33], v[212:219], v[98:101], v187, v187 op_sel_hi:[0,0,0]
	s_setprio 0
	s_barrier
	s_add_i32 s52, s54, s71
	v_lshl_add_u64 v[174:175], v[174:175], 0, s[18:19]
	s_mov_b32 m0, s52
	ds_read_b128 v[188:191], v186 offset:49152
	ds_read_b128 v[192:195], v186 offset:50176
	ds_read_b128 v[196:199], v186 offset:51200
	ds_read_b128 v[200:203], v186 offset:52224
	ds_read_b128 v[204:207], v186 offset:53248
	ds_read_b128 v[208:211], v186 offset:54272
	ds_read_b128 v[212:215], v186 offset:55296
	ds_read_b128 v[216:219], v186 offset:56320
	global_load_lds_dwordx4 v[174:175], off
	s_add_i32 m0, s52, 0x2000
	s_add_u32 s52, s76, 0x80080
	v_lshl_add_u64 v[174:175], v[176:177], 0, s[18:19]
	s_addc_u32 s53, s77, 0
	s_add_i32 s54, s55, s71
	global_load_lds_dwordx4 v[174:175], off
	v_lshl_add_u64 v[174:175], s[52:53], 0, v[164:165]
	s_mov_b32 m0, s54
	s_nop 0
	global_load_lds_dwordx4 v[174:175], off
	v_lshl_add_u64 v[174:175], s[52:53], 0, v[168:169]
	s_add_i32 m0, s54, 0x2000
	s_nop 0
	global_load_lds_dwordx4 v[174:175], off
	v_lshl_add_u64 v[174:175], v[178:179], 0, s[18:19]
	s_mov_b32 m0, s83
	s_nop 0
	global_load_lds_dwordx4 v[174:175], off
	v_lshl_add_u64 v[174:175], v[180:181], 0, s[18:19]
	s_mov_b32 m0, s84
	s_nop 0
	global_load_lds_dwordx4 v[174:175], off
	s_waitcnt vmcnt(8)
	s_waitcnt lgkmcnt(0)
	s_barrier
	s_setprio 1
	s_waitcnt lgkmcnt(0)
	v_mfma_scale_f32_16x16x128_f8f6f4 v[94:97], v[2:9], v[188:195], v[94:97], v187, v187 op_sel_hi:[0,0,0]
	v_mfma_scale_f32_16x16x128_f8f6f4 v[90:93], v[10:17], v[188:195], v[90:93], v187, v187 op_sel_hi:[0,0,0]
	v_mfma_scale_f32_16x16x128_f8f6f4 v[82:85], v[2:9], v[196:203], v[82:85], v187, v187 op_sel_hi:[0,0,0]
	v_mfma_scale_f32_16x16x128_f8f6f4 v[74:77], v[10:17], v[196:203], v[74:77], v187, v187 op_sel_hi:[0,0,0]
	v_mfma_scale_f32_16x16x128_f8f6f4 v[66:69], v[2:9], v[204:211], v[66:69], v187, v187 op_sel_hi:[0,0,0]
	v_mfma_scale_f32_16x16x128_f8f6f4 v[58:61], v[10:17], v[204:211], v[58:61], v187, v187 op_sel_hi:[0,0,0]
	v_mfma_scale_f32_16x16x128_f8f6f4 v[50:53], v[2:9], v[212:219], v[50:53], v187, v187 op_sel_hi:[0,0,0]
	v_mfma_scale_f32_16x16x128_f8f6f4 v[42:45], v[10:17], v[212:219], v[42:45], v187, v187 op_sel_hi:[0,0,0]
	s_setprio 0
	s_setprio 1
	v_mfma_scale_f32_16x16x128_f8f6f4 v[86:89], v[18:25], v[188:195], v[86:89], v187, v187 op_sel_hi:[0,0,0]
	s_add_u32 s60, s60, 0x100
	v_mfma_scale_f32_16x16x128_f8f6f4 v[78:81], v[26:33], v[188:195], v[78:81], v187, v187 op_sel_hi:[0,0,0]
	s_addc_u32 s61, s61, 0
	v_mfma_scale_f32_16x16x128_f8f6f4 v[70:73], v[18:25], v[196:203], v[70:73], v187, v187 op_sel_hi:[0,0,0]
	s_add_u32 vcc_lo, vcc_lo, 0x100
	v_mfma_scale_f32_16x16x128_f8f6f4 v[62:65], v[26:33], v[196:203], v[62:65], v187, v187 op_sel_hi:[0,0,0]
	s_addc_u32 vcc_hi, vcc_hi, 0
	v_mfma_scale_f32_16x16x128_f8f6f4 v[54:57], v[18:25], v[204:211], v[54:57], v187, v187 op_sel_hi:[0,0,0]
	s_cmp_ge_i32 s10, s72
	v_mfma_scale_f32_16x16x128_f8f6f4 v[46:49], v[26:33], v[204:211], v[46:49], v187, v187 op_sel_hi:[0,0,0]
	s_mov_b32 s76, s10
	v_mfma_scale_f32_16x16x128_f8f6f4 v[38:41], v[18:25], v[212:219], v[38:41], v187, v187 op_sel_hi:[0,0,0]
	v_mfma_scale_f32_16x16x128_f8f6f4 v[34:37], v[26:33], v[212:219], v[34:37], v187, v187 op_sel_hi:[0,0,0]
	s_setprio 0
	s_barrier
	s_cbranch_scc0 .LBB0_804
	s_and_b64 vcc, exec, s[20:21]
	s_cbranch_vccz .LBB0_807
	s_barrier

; #define PG8_STAGE(bufoff, gbase, voff) do { _Pragma("unroll") for (int _i = 0; _i < 2; ++_i) \
;         __builtin_amdgcn_global_load_lds((const unsigned*)((const char*)(gbase) + (voff)[_i]), (PG8_LAS unsigned*)(lds + (bufoff) + ldsw + _i * 8192), 16, 0, 0); } while (0)
; #define PG8_LDA(dst, b, h) do { _Pragma("unroll") for (int m = 0; m < 4; ++m) frag_load<F8>(dst[m], lds + PG8_SA(b, h) + aoff + m * 2048); } while (0)
; #define PG8_LDB(dst, b, h) do { _Pragma("unroll") for (int n = 0; n < 2; ++n) frag_load<F8>(dst[n], lds + PG8_SB(b, h) + boff + n * 2048); } while (0)
; #define PG8_MMA(ai, bj, At, Bt) do { __builtin_amdgcn_s_setprio(1); _Pragma("unroll") for (int m = 0; m < 4; ++m) _Pragma("unroll") for (int n = 0; n < 2; ++n) frag_mma<F8>(acc[ai][bj][m][n], Bt[n], At[m]); \
;         __builtin_amdgcn_s_setprio(0); } while (0)
; #define PG8_WAIT_V(n) asm volatile("s_waitcnt vmcnt(" #n ")" ::: "memory")
; #define PG8_WAIT_L(n) asm volatile("s_waitcnt lgkmcnt(" #n ")" ::: "memory")
; #define PG8_BAR __builtin_amdgcn_s_barrier()
; #define PG8_SCHED __builtin_amdgcn_sched_barrier(0)
; template <bool F8, class Epi, class Sched>
; __device__ __forceinline__ void gemm_phase(PG8_LAS unsigned char* lds, const Gemm g, const Sched& S, const Epi& E
;     , unsigned long long* stq = nullptr
;     ) {
;     ...
;             const char* a1 = cA + (size_t)(t + 1) * kstep;
;             const char* a2 = last ? nA : cA + (size_t)(t + 2) * kstep; const char* b2 = last ? nB : cB + (size_t)(t + 2) * kstep;
;             const char* a3 = a2 + kstep; const char* b3 = b2 + kstep;
;             PG8_LDB(B0, 0, 0); PG8_LDB(B1, 0, 1); PG8_SCHED; PG8_LDA(At, 0, 0); PG8_STAGE(PG8_SA(1, 1), a1 + hstepA, voffA);
;             PG8_WAIT_V(8); PG8_WAIT_L(0); PG8_BAR; PG8_MMA(0, 0, At, B0); PG8_MMA(0, 1, At, B1); PG8_BAR; PG8_SCHED;
;             if (!hf) PG8_LDA(At, 0, 1); PG8_STAGE(PG8_SB(0, 0), b2, voffB); PG8_STAGE(PG8_SB(0, 1), b2 + hstepB, voffB); PG8_STAGE(PG8_SA(0, 0), a2, voffA);
;             PG8_WAIT_V(8); PG8_WAIT_L(0); PG8_BAR; if (!hf) { PG8_MMA(1, 0, At, B0); PG8_MMA(1, 1, At, B1); } PG8_BAR; PG8_SCHED;
.LBB0_937:
	ds_read_b128 v[18:21], v188
	ds_read_b128 v[22:25], v188 offset:1024
	ds_read_b128 v[26:29], v188 offset:2048
	ds_read_b128 v[30:33], v188 offset:3072
	ds_read_b128 v[2:5], v189
	ds_read_b128 v[6:9], v189 offset:1024
	ds_read_b128 v[10:13], v189 offset:2048
	ds_read_b128 v[14:17], v189 offset:3072
	s_add_u32 s10, s52, 0xfffc0080
	s_addc_u32 s54, s53, -1
	s_cmp_eq_u32 s84, 12
	s_cselect_b32 s57, s72, s54
	s_cselect_b32 s56, s80, s10
	s_cselect_b32 s55, s37, s83
	s_cselect_b32 s54, s81, s82
	v_lshl_add_u64 v[218:219], s[52:53], 0, v[170:171]
	s_add_i32 m0, s58, 0xc000
	ds_read_b128 v[178:181], v190
	ds_read_b128 v[182:185], v190 offset:1024
	ds_read_b128 v[194:197], v190 offset:2048
	ds_read_b128 v[198:201], v190 offset:3072
	ds_read_b128 v[202:205], v190 offset:4096
	ds_read_b128 v[206:209], v190 offset:5120
	ds_read_b128 v[210:213], v190 offset:6144
	ds_read_b128 v[214:217], v190 offset:7168
	global_load_lds_dwordx4 v[218:219], off
	v_lshl_add_u64 v[218:219], s[52:53], 0, v[172:173]
	s_add_i32 m0, s58, 0xe000
	s_nop 0
	global_load_lds_dwordx4 v[218:219], off
	s_waitcnt vmcnt(8)
	s_waitcnt lgkmcnt(0)
	s_barrier
	s_setprio 1
	s_waitcnt lgkmcnt(0)
	v_mfma_scale_f32_16x16x128_f8f6f4 v[154:157], v[18:25], v[178:185], v[154:157], v191, v191 op_sel_hi:[0,0,0]
	v_mfma_scale_f32_16x16x128_f8f6f4 v[158:161], v[26:33], v[178:185], v[158:161], v191, v191 op_sel_hi:[0,0,0]
	v_mfma_scale_f32_16x16x128_f8f6f4 v[146:149], v[18:25], v[194:201], v[146:149], v191, v191 op_sel_hi:[0,0,0]
	v_mfma_scale_f32_16x16x128_f8f6f4 v[150:153], v[26:33], v[194:201], v[150:153], v191, v191 op_sel_hi:[0,0,0]
	v_mfma_scale_f32_16x16x128_f8f6f4 v[122:125], v[18:25], v[202:209], v[122:125], v191, v191 op_sel_hi:[0,0,0]
	v_mfma_scale_f32_16x16x128_f8f6f4 v[126:129], v[26:33], v[202:209], v[126:129], v191, v191 op_sel_hi:[0,0,0]
	v_mfma_scale_f32_16x16x128_f8f6f4 v[114:117], v[18:25], v[210:217], v[114:117], v191, v191 op_sel_hi:[0,0,0]
	v_mfma_scale_f32_16x16x128_f8f6f4 v[118:121], v[26:33], v[210:217], v[118:121], v191, v191 op_sel_hi:[0,0,0]
	s_setprio 0
	s_setprio 1
	v_mfma_scale_f32_16x16x128_f8f6f4 v[142:145], v[2:9], v[178:185], v[142:145], v191, v191 op_sel_hi:[0,0,0]
	v_mfma_scale_f32_16x16x128_f8f6f4 v[138:141], v[10:17], v[178:185], v[138:141], v191, v191 op_sel_hi:[0,0,0]
	v_mfma_scale_f32_16x16x128_f8f6f4 v[134:137], v[2:9], v[194:201], v[134:137], v191, v191 op_sel_hi:[0,0,0]
	v_mfma_scale_f32_16x16x128_f8f6f4 v[130:133], v[10:17], v[194:201], v[130:133], v191, v191 op_sel_hi:[0,0,0]
	v_mfma_scale_f32_16x16x128_f8f6f4 v[110:113], v[2:9], v[202:209], v[110:113], v191, v191 op_sel_hi:[0,0,0]
	v_mfma_scale_f32_16x16x128_f8f6f4 v[106:109], v[10:17], v[202:209], v[106:109], v191, v191 op_sel_hi:[0,0,0]
	v_mfma_scale_f32_16x16x128_f8f6f4 v[102:105], v[2:9], v[210:217], v[102:105], v191, v191 op_sel_hi:[0,0,0]
	v_mfma_scale_f32_16x16x128_f8f6f4 v[98:101], v[10:17], v[210:217], v[98:101], v191, v191 op_sel_hi:[0,0,0]
	s_setprio 0
	s_barrier
	s_add_i32 s10, s75, s21
	v_lshl_add_u64 v[178:179], s[54:55], 0, v[166:167]
	s_mov_b32 m0, s10
	ds_read_b128 v[194:197], v190 offset:16384
	ds_read_b128 v[198:201], v190 offset:17408
	ds_read_b128 v[202:205], v190 offset:18432
	ds_read_b128 v[206:209], v190 offset:19456
	ds_read_b128 v[210:213], v190 offset:20480
	ds_read_b128 v[214:217], v190 offset:21504
	ds_read_b128 v[222:225], v190 offset:22528
	ds_read_b128 v[226:229], v190 offset:23552
	global_load_lds_dwordx4 v[178:179], off
	s_add_i32 m0, s10, 0x2000
	s_add_u32 s62, s54, 0x40000
	v_lshl_add_u64 v[180:181], s[54:55], 0, v[162:163]
	s_addc_u32 s63, s55, 0
	s_add_i32 s10, s76, s21
	global_load_lds_dwordx4 v[180:181], off
	v_lshl_add_u64 v[182:183], s[62:63], 0, v[166:167]
	s_mov_b32 m0, s10
	v_lshl_add_u64 v[184:185], s[56:57], 0, v[164:165]
	global_load_lds_dwordx4 v[182:183], off
	v_lshl_add_u64 v[182:183], s[62:63], 0, v[162:163]
	s_add_i32 m0, s10, 0x2000
	s_nop 0
	global_load_lds_dwordx4 v[182:183], off
	v_lshl_add_u64 v[182:183], s[56:57], 0, v[168:169]
	s_mov_b32 m0, s58
	s_nop 0
	global_load_lds_dwordx4 v[182:183], off
	s_mov_b32 m0, s59
	s_nop 0
	global_load_lds_dwordx4 v[184:185], off
	s_waitcnt vmcnt(8)
	s_waitcnt lgkmcnt(0)
	s_barrier
	s_setprio 1
	s_waitcnt lgkmcnt(0)
	v_mfma_scale_f32_16x16x128_f8f6f4 v[90:93], v[18:25], v[194:201], v[90:93], v191, v191 op_sel_hi:[0,0,0]
	v_mfma_scale_f32_16x16x128_f8f6f4 v[94:97], v[26:33], v[194:201], v[94:97], v191, v191 op_sel_hi:[0,0,0]
	v_mfma_scale_f32_16x16x128_f8f6f4 v[82:85], v[18:25], v[202:209], v[82:85], v191, v191 op_sel_hi:[0,0,0]
	v_mfma_scale_f32_16x16x128_f8f6f4 v[86:89], v[26:33], v[202:209], v[86:89], v191, v191 op_sel_hi:[0,0,0]
	v_mfma_scale_f32_16x16x128_f8f6f4 v[58:61], v[18:25], v[210:217], v[58:61], v191, v191 op_sel_hi:[0,0,0]
	v_mfma_scale_f32_16x16x128_f8f6f4 v[62:65], v[26:33], v[210:217], v[62:65], v191, v191 op_sel_hi:[0,0,0]
	v_mfma_scale_f32_16x16x128_f8f6f4 v[50:53], v[18:25], v[222:229], v[50:53], v191, v191 op_sel_hi:[0,0,0]
	v_mfma_scale_f32_16x16x128_f8f6f4 v[54:57], v[26:33], v[222:229], v[54:57], v191, v191 op_sel_hi:[0,0,0]
	s_setprio 0
	s_setprio 1
	v_mfma_scale_f32_16x16x128_f8f6f4 v[78:81], v[2:9], v[194:201], v[78:81], v191, v191 op_sel_hi:[0,0,0]
	v_mfma_scale_f32_16x16x128_f8f6f4 v[74:77], v[10:17], v[194:201], v[74:77], v191, v191 op_sel_hi:[0,0,0]
	v_mfma_scale_f32_16x16x128_f8f6f4 v[70:73], v[2:9], v[202:209], v[70:73], v191, v191 op_sel_hi:[0,0,0]
	v_mfma_scale_f32_16x16x128_f8f6f4 v[66:69], v[10:17], v[202:209], v[66:69], v191, v191 op_sel_hi:[0,0,0]
	v_mfma_scale_f32_16x16x128_f8f6f4 v[46:49], v[2:9], v[210:217], v[46:49], v191, v191 op_sel_hi:[0,0,0]
	v_mfma_scale_f32_16x16x128_f8f6f4 v[42:45], v[10:17], v[210:217], v[42:45], v191, v191 op_sel_hi:[0,0,0]
	v_mfma_scale_f32_16x16x128_f8f6f4 v[38:41], v[2:9], v[222:229], v[38:41], v191, v191 op_sel_hi:[0,0,0]
	v_mfma_scale_f32_16x16x128_f8f6f4 v[34:37], v[10:17], v[222:229], v[34:37], v191, v191 op_sel_hi:[0,0,0]
	s_setprio 0
	s_barrier
; #define PG8_STAGE(bufoff, gbase, voff) do { _Pragma("unroll") for (int _i = 0; _i < 2; ++_i) \
;         __builtin_amdgcn_global_load_lds((const unsigned*)((const char*)(gbase) + (voff)[_i]), (PG8_LAS unsigned*)(lds + (bufoff) + ldsw + _i * 8192), 16, 0, 0); } while (0)
; #define PG8_LDA(dst, b, h) do { _Pragma("unroll") for (int m = 0; m < 4; ++m) frag_load<F8>(dst[m], lds + PG8_SA(b, h) + aoff + m * 2048); } while (0)
; #define PG8_LDB(dst, b, h) do { _Pragma("unroll") for (int n = 0; n < 2; ++n) frag_load<F8>(dst[n], lds + PG8_SB(b, h) + boff + n * 2048); } while (0)
; #define PG8_MMA(ai, bj, At, Bt) do { __builtin_amdgcn_s_setprio(1); _Pragma("unroll") for (int m = 0; m < 4; ++m) _Pragma("unroll") for (int n = 0; n < 2; ++n) frag_mma<F8>(acc[ai][bj][m][n], Bt[n], At[m]); \
;         __builtin_amdgcn_s_setprio(0); } while (0)
; #define PG8_WAIT_V(n) asm volatile("s_waitcnt vmcnt(" #n ")" ::: "memory")
; #define PG8_WAIT_L(n) asm volatile("s_waitcnt lgkmcnt(" #n ")" ::: "memory")
; #define PG8_BAR __builtin_amdgcn_s_barrier()
; #define PG8_SCHED __builtin_amdgcn_sched_barrier(0)
; template <bool F8, class Epi, class Sched>
; __device__ __forceinline__ void gemm_phase(PG8_LAS unsigned char* lds, const Gemm g, const Sched& S, const Epi& E
;     , unsigned long long* stq = nullptr
;     ) {
;     ...
;             PG8_LDB(B0, 1, 0); PG8_LDB(B1, 1, 1); PG8_SCHED; PG8_LDA(At, 1, 0); PG8_STAGE(PG8_SA(0, 1), a2 + hstepA, voffA);
;             PG8_WAIT_V(8); PG8_WAIT_L(0); PG8_BAR; PG8_MMA(0, 0, At, B0); PG8_MMA(0, 1, At, B1); PG8_BAR; PG8_SCHED;
;             if (!hf) PG8_LDA(At, 1, 1); PG8_STAGE(PG8_SB(1, 0), b3, voffB); PG8_STAGE(PG8_SB(1, 1), b3 + hstepB, voffB); PG8_STAGE(PG8_SA(1, 0), a3, voffA);
;             PG8_WAIT_V(8); PG8_WAIT_L(0); PG8_BAR; if (!hf) { PG8_MMA(1, 0, At, B0); PG8_MMA(1, 1, At, B1); } PG8_BAR; PG8_SCHED;
;         }
	s_add_i32 s10, 0, 0x18000
	s_add_i32 s62, 0, 0x1c000
	v_add_u32_e32 v14, s10, v186
	v_add_u32_e32 v30, s62, v186
	ds_read_b128 v[2:5], v14
	ds_read_b128 v[6:9], v14 offset:1024
	ds_read_b128 v[10:13], v14 offset:2048
	ds_read_b128 v[14:17], v14 offset:3072
	ds_read_b128 v[18:21], v30
	ds_read_b128 v[22:25], v30 offset:1024
	ds_read_b128 v[26:29], v30 offset:2048
	ds_read_b128 v[30:33], v30 offset:3072
	s_add_u32 s56, s56, 0x40000
	s_addc_u32 s57, s57, 0
	s_mov_b32 m0, s60
	v_lshl_add_u64 v[218:219], s[56:57], 0, v[168:169]
	ds_read_b128 v[194:197], v190 offset:32768
	ds_read_b128 v[198:201], v190 offset:33792
	ds_read_b128 v[202:205], v190 offset:34816
	ds_read_b128 v[206:209], v190 offset:35840
	ds_read_b128 v[210:213], v190 offset:36864
	ds_read_b128 v[214:217], v190 offset:37888
	ds_read_b128 v[222:225], v190 offset:38912
	ds_read_b128 v[226:229], v190 offset:39936
	global_load_lds_dwordx4 v[218:219], off
	v_lshl_add_u64 v[218:219], s[56:57], 0, v[164:165]
	s_mov_b32 m0, s61
	s_nop 0
	global_load_lds_dwordx4 v[218:219], off
	s_waitcnt vmcnt(8)
	s_waitcnt lgkmcnt(0)
	s_barrier
	s_setprio 1
	s_waitcnt lgkmcnt(0)
	v_mfma_scale_f32_16x16x128_f8f6f4 v[154:157], v[2:9], v[194:201], v[154:157], v191, v191 op_sel_hi:[0,0,0]
	v_mfma_scale_f32_16x16x128_f8f6f4 v[158:161], v[10:17], v[194:201], v[158:161], v191, v191 op_sel_hi:[0,0,0]
	v_mfma_scale_f32_16x16x128_f8f6f4 v[146:149], v[2:9], v[202:209], v[146:149], v191, v191 op_sel_hi:[0,0,0]
	v_mfma_scale_f32_16x16x128_f8f6f4 v[150:153], v[10:17], v[202:209], v[150:153], v191, v191 op_sel_hi:[0,0,0]
	v_mfma_scale_f32_16x16x128_f8f6f4 v[122:125], v[2:9], v[210:217], v[122:125], v191, v191 op_sel_hi:[0,0,0]
	v_mfma_scale_f32_16x16x128_f8f6f4 v[126:129], v[10:17], v[210:217], v[126:129], v191, v191 op_sel_hi:[0,0,0]
	v_mfma_scale_f32_16x16x128_f8f6f4 v[114:117], v[2:9], v[222:229], v[114:117], v191, v191 op_sel_hi:[0,0,0]
	v_mfma_scale_f32_16x16x128_f8f6f4 v[118:121], v[10:17], v[222:229], v[118:121], v191, v191 op_sel_hi:[0,0,0]
	s_setprio 0
	s_setprio 1
	v_mfma_scale_f32_16x16x128_f8f6f4 v[142:145], v[18:25], v[194:201], v[142:145], v191, v191 op_sel_hi:[0,0,0]
	v_mfma_scale_f32_16x16x128_f8f6f4 v[138:141], v[26:33], v[194:201], v[138:141], v191, v191 op_sel_hi:[0,0,0]
	v_mfma_scale_f32_16x16x128_f8f6f4 v[134:137], v[18:25], v[202:209], v[134:137], v191, v191 op_sel_hi:[0,0,0]
	v_mfma_scale_f32_16x16x128_f8f6f4 v[130:133], v[26:33], v[202:209], v[130:133], v191, v191 op_sel_hi:[0,0,0]
	v_mfma_scale_f32_16x16x128_f8f6f4 v[110:113], v[18:25], v[210:217], v[110:113], v191, v191 op_sel_hi:[0,0,0]
	v_mfma_scale_f32_16x16x128_f8f6f4 v[106:109], v[26:33], v[210:217], v[106:109], v191, v191 op_sel_hi:[0,0,0]
	v_mfma_scale_f32_16x16x128_f8f6f4 v[102:105], v[18:25], v[222:229], v[102:105], v191, v191 op_sel_hi:[0,0,0]
	v_mfma_scale_f32_16x16x128_f8f6f4 v[98:101], v[26:33], v[222:229], v[98:101], v191, v191 op_sel_hi:[0,0,0]
	s_setprio 0
	s_barrier
	s_add_i32 s10, s10, s21
	v_lshl_add_u64 v[178:179], v[178:179], 0, s[16:17]
	s_mov_b32 m0, s10
	ds_read_b128 v[194:197], v190 offset:49152
	ds_read_b128 v[198:201], v190 offset:50176
	ds_read_b128 v[202:205], v190 offset:51200
	ds_read_b128 v[206:209], v190 offset:52224
	ds_read_b128 v[210:213], v190 offset:53248
	ds_read_b128 v[214:217], v190 offset:54272
	ds_read_b128 v[222:225], v190 offset:55296
	ds_read_b128 v[226:229], v190 offset:56320
	global_load_lds_dwordx4 v[178:179], off
	s_add_i32 m0, s10, 0x2000
	s_add_u32 s54, s54, 0x40080
	v_lshl_add_u64 v[178:179], v[180:181], 0, s[16:17]
	s_addc_u32 s55, s55, 0
	s_add_i32 s10, s62, s21
	global_load_lds_dwordx4 v[178:179], off
	v_lshl_add_u64 v[178:179], s[54:55], 0, v[166:167]
	s_mov_b32 m0, s10
	s_nop 0
	global_load_lds_dwordx4 v[178:179], off
	v_lshl_add_u64 v[178:179], s[54:55], 0, v[162:163]
	s_add_i32 m0, s10, 0x2000
	s_nop 0
	global_load_lds_dwordx4 v[178:179], off
	v_lshl_add_u64 v[178:179], v[182:183], 0, s[16:17]
	s_mov_b32 m0, s71
	s_nop 0
	global_load_lds_dwordx4 v[178:179], off
	v_lshl_add_u64 v[178:179], v[184:185], 0, s[16:17]
	s_mov_b32 m0, s73
	s_nop 0
	global_load_lds_dwordx4 v[178:179], off
	s_waitcnt vmcnt(8)
	s_waitcnt lgkmcnt(0)
	s_barrier
	s_setprio 1
	s_waitcnt lgkmcnt(0)
	v_mfma_scale_f32_16x16x128_f8f6f4 v[90:93], v[2:9], v[194:201], v[90:93], v191, v191 op_sel_hi:[0,0,0]
	v_mfma_scale_f32_16x16x128_f8f6f4 v[94:97], v[10:17], v[194:201], v[94:97], v191, v191 op_sel_hi:[0,0,0]
	v_mfma_scale_f32_16x16x128_f8f6f4 v[82:85], v[2:9], v[202:209], v[82:85], v191, v191 op_sel_hi:[0,0,0]
	v_mfma_scale_f32_16x16x128_f8f6f4 v[86:89], v[10:17], v[202:209], v[86:89], v191, v191 op_sel_hi:[0,0,0]
	v_mfma_scale_f32_16x16x128_f8f6f4 v[58:61], v[2:9], v[210:217], v[58:61], v191, v191 op_sel_hi:[0,0,0]
	v_mfma_scale_f32_16x16x128_f8f6f4 v[62:65], v[10:17], v[210:217], v[62:65], v191, v191 op_sel_hi:[0,0,0]
	v_mfma_scale_f32_16x16x128_f8f6f4 v[50:53], v[2:9], v[222:229], v[50:53], v191, v191 op_sel_hi:[0,0,0]
	v_mfma_scale_f32_16x16x128_f8f6f4 v[54:57], v[10:17], v[222:229], v[54:57], v191, v191 op_sel_hi:[0,0,0]
	s_setprio 0
	s_setprio 1
	v_mfma_scale_f32_16x16x128_f8f6f4 v[78:81], v[18:25], v[194:201], v[78:81], v191, v191 op_sel_hi:[0,0,0]
	s_add_i32 s84, s84, 2
	v_mfma_scale_f32_16x16x128_f8f6f4 v[74:77], v[26:33], v[194:201], v[74:77], v191, v191 op_sel_hi:[0,0,0]
	s_add_u32 s52, s52, 0x100
	v_mfma_scale_f32_16x16x128_f8f6f4 v[70:73], v[18:25], v[202:209], v[70:73], v191, v191 op_sel_hi:[0,0,0]
	s_addc_u32 s53, s53, 0
	v_mfma_scale_f32_16x16x128_f8f6f4 v[66:69], v[26:33], v[202:209], v[66:69], v191, v191 op_sel_hi:[0,0,0]
	s_add_u32 s82, s82, 0x100
	v_mfma_scale_f32_16x16x128_f8f6f4 v[46:49], v[18:25], v[210:217], v[46:49], v191, v191 op_sel_hi:[0,0,0]
	s_addc_u32 s83, s83, 0
	v_mfma_scale_f32_16x16x128_f8f6f4 v[42:45], v[26:33], v[210:217], v[42:45], v191, v191 op_sel_hi:[0,0,0]
	s_cmp_gt_u32 s84, 13
	v_mfma_scale_f32_16x16x128_f8f6f4 v[38:41], v[18:25], v[222:229], v[38:41], v191, v191 op_sel_hi:[0,0,0]
	v_mfma_scale_f32_16x16x128_f8f6f4 v[34:37], v[26:33], v[222:229], v[34:37], v191, v191 op_sel_hi:[0,0,0]
	s_setprio 0
	s_barrier
	s_cbranch_scc0 .LBB0_937
	s_and_b64 vcc, exec, s[18:19]
	s_cbranch_vccz .LBB0_940
	s_barrier

; #define PG8_STAGE(bufoff, gbase, voff) do { _Pragma("unroll") for (int _i = 0; _i < 2; ++_i) \
;         __builtin_amdgcn_global_load_lds((const unsigned*)((const char*)(gbase) + (voff)[_i]), (PG8_LAS unsigned*)(lds + (bufoff) + ldsw + _i * 8192), 16, 0, 0); } while (0)
; #define PG8_LDA(dst, b, h) do { _Pragma("unroll") for (int m = 0; m < 4; ++m) frag_load<F8>(dst[m], lds + PG8_SA(b, h) + aoff + m * 2048); } while (0)
; #define PG8_LDB(dst, b, h) do { _Pragma("unroll") for (int n = 0; n < 2; ++n) frag_load<F8>(dst[n], lds + PG8_SB(b, h) + boff + n * 2048); } while (0)
; #define PG8_MMA(ai, bj, At, Bt) do { __builtin_amdgcn_s_setprio(1); _Pragma("unroll") for (int m = 0; m < 4; ++m) _Pragma("unroll") for (int n = 0; n < 2; ++n) frag_mma<F8>(acc[ai][bj][m][n], Bt[n], At[m]); \
;         __builtin_amdgcn_s_setprio(0); } while (0)
; #define PG8_WAIT_V(n) asm volatile("s_waitcnt vmcnt(" #n ")" ::: "memory")
; #define PG8_WAIT_L(n) asm volatile("s_waitcnt lgkmcnt(" #n ")" ::: "memory")
; #define PG8_BAR __builtin_amdgcn_s_barrier()
; #define PG8_SCHED __builtin_amdgcn_sched_barrier(0)
; template <bool F8, class Epi, class Sched>
; __device__ __forceinline__ void gemm_phase(PG8_LAS unsigned char* lds, const Gemm g, const Sched& S, const Epi& E
;     , unsigned long long* stq = nullptr
;     ) {
;     ...
;             const char* a1 = cA + (size_t)(t + 1) * kstep;
;             const char* a2 = last ? nA : cA + (size_t)(t + 2) * kstep; const char* b2 = last ? nB : cB + (size_t)(t + 2) * kstep;
;             const char* a3 = a2 + kstep; const char* b3 = b2 + kstep;
;             PG8_LDB(B0, 0, 0); PG8_LDB(B1, 0, 1); PG8_SCHED; PG8_LDA(At, 0, 0); PG8_STAGE(PG8_SA(1, 1), a1 + hstepA, voffA);
;             PG8_WAIT_V(8); PG8_WAIT_L(0); PG8_BAR; PG8_MMA(0, 0, At, B0); PG8_MMA(0, 1, At, B1); PG8_BAR; PG8_SCHED;
;             if (!hf) PG8_LDA(At, 0, 1); PG8_STAGE(PG8_SB(0, 0), b2, voffB); PG8_STAGE(PG8_SB(0, 1), b2 + hstepB, voffB); PG8_STAGE(PG8_SA(0, 0), a2, voffA);
;             PG8_WAIT_V(8); PG8_WAIT_L(0); PG8_BAR; if (!hf) { PG8_MMA(1, 0, At, B0); PG8_MMA(1, 1, At, B1); } PG8_BAR; PG8_SCHED;
.LBB0_1137:
	ds_read_b128 v[18:21], v184
	ds_read_b128 v[22:25], v184 offset:1024
	ds_read_b128 v[26:29], v184 offset:2048
	ds_read_b128 v[30:33], v184 offset:3072
	s_waitcnt lgkmcnt(0)
	ds_read_b128 v[2:5], v185
	ds_read_b128 v[6:9], v185 offset:1024
	ds_read_b128 v[10:13], v185 offset:2048
	ds_read_b128 v[14:17], v185 offset:3072
	s_add_i32 s10, s76, 2
	s_add_u32 s62, s60, 0xfff50080
	s_addc_u32 s63, s61, -1
	s_cmp_eq_u32 s93, s76
	s_cselect_b32 s76, s58, s94
	s_cselect_b32 s79, s57, s63
	s_cselect_b32 s78, s56, s62
	s_cselect_b32 s77, s59, s95
	v_lshl_add_u64 v[214:215], s[60:61], 0, v[170:171]
	s_add_i32 m0, s71, 0xc000
	ds_read_b128 v[174:177], v186
	ds_read_b128 v[178:181], v186 offset:1024
	ds_read_b128 v[190:193], v186 offset:2048
	ds_read_b128 v[194:197], v186 offset:3072
	ds_read_b128 v[198:201], v186 offset:4096
	ds_read_b128 v[202:205], v186 offset:5120
	ds_read_b128 v[206:209], v186 offset:6144
	ds_read_b128 v[210:213], v186 offset:7168
	global_load_lds_dwordx4 v[214:215], off
	v_lshl_add_u64 v[214:215], s[60:61], 0, v[172:173]
	s_add_i32 m0, s71, 0xe000
	s_nop 0
	global_load_lds_dwordx4 v[214:215], off
	s_waitcnt vmcnt(8)
	s_waitcnt lgkmcnt(0)
	s_barrier
	s_setprio 1
	s_waitcnt lgkmcnt(0)
	v_mfma_scale_f32_16x16x128_f8f6f4 v[158:161], v[18:25], v[174:181], v[158:161], v187, v187 op_sel_hi:[0,0,0]
	v_mfma_scale_f32_16x16x128_f8f6f4 v[154:157], v[26:33], v[174:181], v[154:157], v187, v187 op_sel_hi:[0,0,0]
	v_mfma_scale_f32_16x16x128_f8f6f4 v[146:149], v[18:25], v[190:197], v[146:149], v187, v187 op_sel_hi:[0,0,0]
	v_mfma_scale_f32_16x16x128_f8f6f4 v[138:141], v[26:33], v[190:197], v[138:141], v187, v187 op_sel_hi:[0,0,0]
	v_mfma_scale_f32_16x16x128_f8f6f4 v[130:133], v[18:25], v[198:205], v[130:133], v187, v187 op_sel_hi:[0,0,0]
	v_mfma_scale_f32_16x16x128_f8f6f4 v[122:125], v[26:33], v[198:205], v[122:125], v187, v187 op_sel_hi:[0,0,0]
	v_mfma_scale_f32_16x16x128_f8f6f4 v[114:117], v[18:25], v[206:213], v[114:117], v187, v187 op_sel_hi:[0,0,0]
	v_mfma_scale_f32_16x16x128_f8f6f4 v[106:109], v[26:33], v[206:213], v[106:109], v187, v187 op_sel_hi:[0,0,0]
	s_setprio 0
	s_setprio 1
	v_mfma_scale_f32_16x16x128_f8f6f4 v[150:153], v[2:9], v[174:181], v[150:153], v187, v187 op_sel_hi:[0,0,0]
	v_mfma_scale_f32_16x16x128_f8f6f4 v[142:145], v[10:17], v[174:181], v[142:145], v187, v187 op_sel_hi:[0,0,0]
	v_mfma_scale_f32_16x16x128_f8f6f4 v[134:137], v[2:9], v[190:197], v[134:137], v187, v187 op_sel_hi:[0,0,0]
	v_mfma_scale_f32_16x16x128_f8f6f4 v[126:129], v[10:17], v[190:197], v[126:129], v187, v187 op_sel_hi:[0,0,0]
	v_mfma_scale_f32_16x16x128_f8f6f4 v[118:121], v[2:9], v[198:205], v[118:121], v187, v187 op_sel_hi:[0,0,0]
	v_mfma_scale_f32_16x16x128_f8f6f4 v[110:113], v[10:17], v[198:205], v[110:113], v187, v187 op_sel_hi:[0,0,0]
	v_mfma_scale_f32_16x16x128_f8f6f4 v[102:105], v[2:9], v[206:213], v[102:105], v187, v187 op_sel_hi:[0,0,0]
	v_mfma_scale_f32_16x16x128_f8f6f4 v[98:101], v[10:17], v[206:213], v[98:101], v187, v187 op_sel_hi:[0,0,0]
	s_setprio 0
	s_barrier
	s_add_i32 s62, s84, s70
	v_lshl_add_u64 v[174:175], s[76:77], 0, v[164:165]
	s_mov_b32 m0, s62
	ds_read_b128 v[190:193], v186 offset:16384
	ds_read_b128 v[194:197], v186 offset:17408
	ds_read_b128 v[198:201], v186 offset:18432
	ds_read_b128 v[202:205], v186 offset:19456
	ds_read_b128 v[206:209], v186 offset:20480
	ds_read_b128 v[210:213], v186 offset:21504
	ds_read_b128 v[222:225], v186 offset:22528
	ds_read_b128 v[226:229], v186 offset:23552
	global_load_lds_dwordx4 v[174:175], off
	s_add_i32 m0, s62, 0x2000
	s_add_u32 s62, s76, 0xb0000
	v_lshl_add_u64 v[176:177], s[76:77], 0, v[168:169]
	s_addc_u32 s63, s77, 0
	s_add_i32 s64, s85, s70
	global_load_lds_dwordx4 v[176:177], off
	v_lshl_add_u64 v[178:179], s[62:63], 0, v[164:165]
	s_mov_b32 m0, s64
	v_lshl_add_u64 v[180:181], s[78:79], 0, v[166:167]
	global_load_lds_dwordx4 v[178:179], off
	v_lshl_add_u64 v[178:179], s[62:63], 0, v[168:169]
	s_add_i32 m0, s64, 0x2000
	s_nop 0
	global_load_lds_dwordx4 v[178:179], off
	v_lshl_add_u64 v[178:179], s[78:79], 0, v[162:163]
	s_mov_b32 m0, s71
	s_nop 0
	global_load_lds_dwordx4 v[178:179], off
	s_mov_b32 m0, s73
	s_nop 0
	global_load_lds_dwordx4 v[180:181], off
	s_waitcnt vmcnt(8)
	s_waitcnt lgkmcnt(0)
	s_barrier
	s_setprio 1
	s_waitcnt lgkmcnt(0)
	v_mfma_scale_f32_16x16x128_f8f6f4 v[94:97], v[18:25], v[190:197], v[94:97], v187, v187 op_sel_hi:[0,0,0]
	v_mfma_scale_f32_16x16x128_f8f6f4 v[90:93], v[26:33], v[190:197], v[90:93], v187, v187 op_sel_hi:[0,0,0]
	v_mfma_scale_f32_16x16x128_f8f6f4 v[82:85], v[18:25], v[198:205], v[82:85], v187, v187 op_sel_hi:[0,0,0]
	v_mfma_scale_f32_16x16x128_f8f6f4 v[74:77], v[26:33], v[198:205], v[74:77], v187, v187 op_sel_hi:[0,0,0]
	v_mfma_scale_f32_16x16x128_f8f6f4 v[66:69], v[18:25], v[206:213], v[66:69], v187, v187 op_sel_hi:[0,0,0]
	v_mfma_scale_f32_16x16x128_f8f6f4 v[58:61], v[26:33], v[206:213], v[58:61], v187, v187 op_sel_hi:[0,0,0]
	v_mfma_scale_f32_16x16x128_f8f6f4 v[50:53], v[18:25], v[222:229], v[50:53], v187, v187 op_sel_hi:[0,0,0]
	v_mfma_scale_f32_16x16x128_f8f6f4 v[42:45], v[26:33], v[222:229], v[42:45], v187, v187 op_sel_hi:[0,0,0]
	s_setprio 0
	s_setprio 1
	v_mfma_scale_f32_16x16x128_f8f6f4 v[86:89], v[2:9], v[190:197], v[86:89], v187, v187 op_sel_hi:[0,0,0]
	v_mfma_scale_f32_16x16x128_f8f6f4 v[78:81], v[10:17], v[190:197], v[78:81], v187, v187 op_sel_hi:[0,0,0]
	v_mfma_scale_f32_16x16x128_f8f6f4 v[70:73], v[2:9], v[198:205], v[70:73], v187, v187 op_sel_hi:[0,0,0]
	v_mfma_scale_f32_16x16x128_f8f6f4 v[62:65], v[10:17], v[198:205], v[62:65], v187, v187 op_sel_hi:[0,0,0]
	v_mfma_scale_f32_16x16x128_f8f6f4 v[54:57], v[2:9], v[206:213], v[54:57], v187, v187 op_sel_hi:[0,0,0]
	v_mfma_scale_f32_16x16x128_f8f6f4 v[46:49], v[10:17], v[206:213], v[46:49], v187, v187 op_sel_hi:[0,0,0]
	v_mfma_scale_f32_16x16x128_f8f6f4 v[38:41], v[2:9], v[222:229], v[38:41], v187, v187 op_sel_hi:[0,0,0]
	v_mfma_scale_f32_16x16x128_f8f6f4 v[34:37], v[10:17], v[222:229], v[34:37], v187, v187 op_sel_hi:[0,0,0]
	s_setprio 0
	s_barrier
; #define PG8_STAGE(bufoff, gbase, voff) do { _Pragma("unroll") for (int _i = 0; _i < 2; ++_i) \
;         __builtin_amdgcn_global_load_lds((const unsigned*)((const char*)(gbase) + (voff)[_i]), (PG8_LAS unsigned*)(lds + (bufoff) + ldsw + _i * 8192), 16, 0, 0); } while (0)
; #define PG8_LDA(dst, b, h) do { _Pragma("unroll") for (int m = 0; m < 4; ++m) frag_load<F8>(dst[m], lds + PG8_SA(b, h) + aoff + m * 2048); } while (0)
; #define PG8_LDB(dst, b, h) do { _Pragma("unroll") for (int n = 0; n < 2; ++n) frag_load<F8>(dst[n], lds + PG8_SB(b, h) + boff + n * 2048); } while (0)
; #define PG8_MMA(ai, bj, At, Bt) do { __builtin_amdgcn_s_setprio(1); _Pragma("unroll") for (int m = 0; m < 4; ++m) _Pragma("unroll") for (int n = 0; n < 2; ++n) frag_mma<F8>(acc[ai][bj][m][n], Bt[n], At[m]); \
;         __builtin_amdgcn_s_setprio(0); } while (0)
; #define PG8_WAIT_V(n) asm volatile("s_waitcnt vmcnt(" #n ")" ::: "memory")
; #define PG8_WAIT_L(n) asm volatile("s_waitcnt lgkmcnt(" #n ")" ::: "memory")
; #define PG8_BAR __builtin_amdgcn_s_barrier()
; #define PG8_SCHED __builtin_amdgcn_sched_barrier(0)
; template <bool F8, class Epi, class Sched>
; __device__ __forceinline__ void gemm_phase(PG8_LAS unsigned char* lds, const Gemm g, const Sched& S, const Epi& E
;     , unsigned long long* stq = nullptr
;     ) {
;     ...
;             PG8_LDB(B0, 1, 0); PG8_LDB(B1, 1, 1); PG8_SCHED; PG8_LDA(At, 1, 0); PG8_STAGE(PG8_SA(0, 1), a2 + hstepA, voffA);
;             PG8_WAIT_V(8); PG8_WAIT_L(0); PG8_BAR; PG8_MMA(0, 0, At, B0); PG8_MMA(0, 1, At, B1); PG8_BAR; PG8_SCHED;
;             if (!hf) PG8_LDA(At, 1, 1); PG8_STAGE(PG8_SB(1, 0), b3, voffB); PG8_STAGE(PG8_SB(1, 1), b3 + hstepB, voffB); PG8_STAGE(PG8_SA(1, 0), a3, voffA);
;             PG8_WAIT_V(8); PG8_WAIT_L(0); PG8_BAR; if (!hf) { PG8_MMA(1, 0, At, B0); PG8_MMA(1, 1, At, B1); } PG8_BAR; PG8_SCHED;
;         }
	s_add_i32 s64, 0, 0x18000
	s_add_i32 s65, 0, 0x1c000
	v_add_u32_e32 v14, s64, v182
	v_add_u32_e32 v30, s65, v182
	ds_read_b128 v[2:5], v14
	ds_read_b128 v[6:9], v14 offset:1024
	ds_read_b128 v[10:13], v14 offset:2048
	ds_read_b128 v[14:17], v14 offset:3072
	ds_read_b128 v[18:21], v30
	ds_read_b128 v[22:25], v30 offset:1024
	ds_read_b128 v[26:29], v30 offset:2048
	ds_read_b128 v[30:33], v30 offset:3072
	s_add_u32 s62, s78, 0xb0000
	s_addc_u32 s63, s79, 0
	s_mov_b32 m0, s74
	v_lshl_add_u64 v[214:215], s[62:63], 0, v[162:163]
	ds_read_b128 v[190:193], v186 offset:32768
	ds_read_b128 v[194:197], v186 offset:33792
	ds_read_b128 v[198:201], v186 offset:34816
	ds_read_b128 v[202:205], v186 offset:35840
	ds_read_b128 v[206:209], v186 offset:36864
	ds_read_b128 v[210:213], v186 offset:37888
	ds_read_b128 v[222:225], v186 offset:38912
	ds_read_b128 v[226:229], v186 offset:39936
	global_load_lds_dwordx4 v[214:215], off
	v_lshl_add_u64 v[214:215], s[62:63], 0, v[166:167]
	s_mov_b32 m0, s75
	s_nop 0
	global_load_lds_dwordx4 v[214:215], off
	s_waitcnt vmcnt(8)
	s_waitcnt lgkmcnt(0)
	s_barrier
	s_setprio 1
	s_waitcnt lgkmcnt(0)
	v_mfma_scale_f32_16x16x128_f8f6f4 v[158:161], v[2:9], v[190:197], v[158:161], v187, v187 op_sel_hi:[0,0,0]
	v_mfma_scale_f32_16x16x128_f8f6f4 v[154:157], v[10:17], v[190:197], v[154:157], v187, v187 op_sel_hi:[0,0,0]
	v_mfma_scale_f32_16x16x128_f8f6f4 v[146:149], v[2:9], v[198:205], v[146:149], v187, v187 op_sel_hi:[0,0,0]
	v_mfma_scale_f32_16x16x128_f8f6f4 v[138:141], v[10:17], v[198:205], v[138:141], v187, v187 op_sel_hi:[0,0,0]
	v_mfma_scale_f32_16x16x128_f8f6f4 v[130:133], v[2:9], v[206:213], v[130:133], v187, v187 op_sel_hi:[0,0,0]
	v_mfma_scale_f32_16x16x128_f8f6f4 v[122:125], v[10:17], v[206:213], v[122:125], v187, v187 op_sel_hi:[0,0,0]
	v_mfma_scale_f32_16x16x128_f8f6f4 v[114:117], v[2:9], v[222:229], v[114:117], v187, v187 op_sel_hi:[0,0,0]
	v_mfma_scale_f32_16x16x128_f8f6f4 v[106:109], v[10:17], v[222:229], v[106:109], v187, v187 op_sel_hi:[0,0,0]
	s_setprio 0
	s_setprio 1
	v_mfma_scale_f32_16x16x128_f8f6f4 v[150:153], v[18:25], v[190:197], v[150:153], v187, v187 op_sel_hi:[0,0,0]
	v_mfma_scale_f32_16x16x128_f8f6f4 v[142:145], v[26:33], v[190:197], v[142:145], v187, v187 op_sel_hi:[0,0,0]
	v_mfma_scale_f32_16x16x128_f8f6f4 v[134:137], v[18:25], v[198:205], v[134:137], v187, v187 op_sel_hi:[0,0,0]
	v_mfma_scale_f32_16x16x128_f8f6f4 v[126:129], v[26:33], v[198:205], v[126:129], v187, v187 op_sel_hi:[0,0,0]
	v_mfma_scale_f32_16x16x128_f8f6f4 v[118:121], v[18:25], v[206:213], v[118:121], v187, v187 op_sel_hi:[0,0,0]
	v_mfma_scale_f32_16x16x128_f8f6f4 v[110:113], v[26:33], v[206:213], v[110:113], v187, v187 op_sel_hi:[0,0,0]
	v_mfma_scale_f32_16x16x128_f8f6f4 v[102:105], v[18:25], v[222:229], v[102:105], v187, v187 op_sel_hi:[0,0,0]
	v_mfma_scale_f32_16x16x128_f8f6f4 v[98:101], v[26:33], v[222:229], v[98:101], v187, v187 op_sel_hi:[0,0,0]
	s_setprio 0
	s_barrier
	s_add_i32 s62, s64, s70
	v_lshl_add_u64 v[174:175], v[174:175], 0, s[38:39]
	s_mov_b32 m0, s62
	ds_read_b128 v[190:193], v186 offset:49152
	ds_read_b128 v[194:197], v186 offset:50176
	ds_read_b128 v[198:201], v186 offset:51200
	ds_read_b128 v[202:205], v186 offset:52224
	ds_read_b128 v[206:209], v186 offset:53248
	ds_read_b128 v[210:213], v186 offset:54272
	ds_read_b128 v[222:225], v186 offset:55296
	ds_read_b128 v[226:229], v186 offset:56320
	global_load_lds_dwordx4 v[174:175], off
	s_add_i32 m0, s62, 0x2000
	s_add_u32 s62, s76, 0xb0080
	v_lshl_add_u64 v[174:175], v[176:177], 0, s[38:39]
	s_addc_u32 s63, s77, 0
	s_add_i32 s64, s65, s70
	global_load_lds_dwordx4 v[174:175], off
	v_lshl_add_u64 v[174:175], s[62:63], 0, v[164:165]
	s_mov_b32 m0, s64
	s_nop 0
	global_load_lds_dwordx4 v[174:175], off
	v_lshl_add_u64 v[174:175], s[62:63], 0, v[168:169]
	s_add_i32 m0, s64, 0x2000
	s_nop 0
	global_load_lds_dwordx4 v[174:175], off
	v_lshl_add_u64 v[174:175], v[178:179], 0, s[38:39]
	s_mov_b32 m0, s82
	s_nop 0
	global_load_lds_dwordx4 v[174:175], off
	v_lshl_add_u64 v[174:175], v[180:181], 0, s[38:39]
	s_mov_b32 m0, s83
	s_nop 0
	global_load_lds_dwordx4 v[174:175], off
	s_waitcnt vmcnt(8)
	s_waitcnt lgkmcnt(0)
	s_barrier
	s_setprio 1
	s_waitcnt lgkmcnt(0)
	v_mfma_scale_f32_16x16x128_f8f6f4 v[94:97], v[2:9], v[190:197], v[94:97], v187, v187 op_sel_hi:[0,0,0]
	v_mfma_scale_f32_16x16x128_f8f6f4 v[90:93], v[10:17], v[190:197], v[90:93], v187, v187 op_sel_hi:[0,0,0]
	v_mfma_scale_f32_16x16x128_f8f6f4 v[82:85], v[2:9], v[198:205], v[82:85], v187, v187 op_sel_hi:[0,0,0]
	v_mfma_scale_f32_16x16x128_f8f6f4 v[74:77], v[10:17], v[198:205], v[74:77], v187, v187 op_sel_hi:[0,0,0]
	v_mfma_scale_f32_16x16x128_f8f6f4 v[66:69], v[2:9], v[206:213], v[66:69], v187, v187 op_sel_hi:[0,0,0]
	v_mfma_scale_f32_16x16x128_f8f6f4 v[58:61], v[10:17], v[206:213], v[58:61], v187, v187 op_sel_hi:[0,0,0]
	v_mfma_scale_f32_16x16x128_f8f6f4 v[50:53], v[2:9], v[222:229], v[50:53], v187, v187 op_sel_hi:[0,0,0]
	v_mfma_scale_f32_16x16x128_f8f6f4 v[42:45], v[10:17], v[222:229], v[42:45], v187, v187 op_sel_hi:[0,0,0]
	s_setprio 0
	s_setprio 1
	v_mfma_scale_f32_16x16x128_f8f6f4 v[86:89], v[18:25], v[190:197], v[86:89], v187, v187 op_sel_hi:[0,0,0]
	s_add_u32 s60, s60, 0x100
	v_mfma_scale_f32_16x16x128_f8f6f4 v[78:81], v[26:33], v[190:197], v[78:81], v187, v187 op_sel_hi:[0,0,0]
	s_addc_u32 s61, s61, 0
	v_mfma_scale_f32_16x16x128_f8f6f4 v[70:73], v[18:25], v[198:205], v[70:73], v187, v187 op_sel_hi:[0,0,0]
	s_add_u32 s94, s94, 0x100
	v_mfma_scale_f32_16x16x128_f8f6f4 v[62:65], v[26:33], v[198:205], v[62:65], v187, v187 op_sel_hi:[0,0,0]
	s_addc_u32 s95, s95, 0
	v_mfma_scale_f32_16x16x128_f8f6f4 v[54:57], v[18:25], v[206:213], v[54:57], v187, v187 op_sel_hi:[0,0,0]
	s_cmp_ge_i32 s10, s72
	v_mfma_scale_f32_16x16x128_f8f6f4 v[46:49], v[26:33], v[206:213], v[46:49], v187, v187 op_sel_hi:[0,0,0]
	s_mov_b32 s76, s10
	v_mfma_scale_f32_16x16x128_f8f6f4 v[38:41], v[18:25], v[222:229], v[38:41], v187, v187 op_sel_hi:[0,0,0]
	v_mfma_scale_f32_16x16x128_f8f6f4 v[34:37], v[26:33], v[222:229], v[34:37], v187, v187 op_sel_hi:[0,0,0]
	s_setprio 0
	s_barrier
	s_cbranch_scc0 .LBB0_1137
	s_and_b64 vcc, exec, s[42:43]
	s_cbranch_vccz .LBB0_1140
	s_barrier

; #define PG8_STAGE(bufoff, gbase, voff) do { _Pragma("unroll") for (int _i = 0; _i < 2; ++_i) \
;         __builtin_amdgcn_global_load_lds((const unsigned*)((const char*)(gbase) + (voff)[_i]), (PG8_LAS unsigned*)(lds + (bufoff) + ldsw + _i * 8192), 16, 0, 0); } while (0)
; #define PG8_LDA(dst, b, h) do { _Pragma("unroll") for (int m = 0; m < 4; ++m) frag_load<F8>(dst[m], lds + PG8_SA(b, h) + aoff + m * 2048); } while (0)
; #define PG8_LDB(dst, b, h) do { _Pragma("unroll") for (int n = 0; n < 2; ++n) frag_load<F8>(dst[n], lds + PG8_SB(b, h) + boff + n * 2048); } while (0)
; #define PG8_MMA(ai, bj, At, Bt) do { __builtin_amdgcn_s_setprio(1); _Pragma("unroll") for (int m = 0; m < 4; ++m) _Pragma("unroll") for (int n = 0; n < 2; ++n) frag_mma<F8>(acc[ai][bj][m][n], Bt[n], At[m]); \
;         __builtin_amdgcn_s_setprio(0); } while (0)
; #define PG8_WAIT_V(n) asm volatile("s_waitcnt vmcnt(" #n ")" ::: "memory")
; #define PG8_WAIT_L(n) asm volatile("s_waitcnt lgkmcnt(" #n ")" ::: "memory")
; #define PG8_BAR __builtin_amdgcn_s_barrier()
; #define PG8_SCHED __builtin_amdgcn_sched_barrier(0)
; template <bool F8, class Epi, class Sched>
; __device__ __forceinline__ void gemm_phase(PG8_LAS unsigned char* lds, const Gemm g, const Sched& S, const Epi& E
;     , unsigned long long* stq = nullptr
;     ) {
;     ...
;             const char* a1 = cA + (size_t)(t + 1) * kstep;
;             const char* a2 = last ? nA : cA + (size_t)(t + 2) * kstep; const char* b2 = last ? nB : cB + (size_t)(t + 2) * kstep;
;             const char* a3 = a2 + kstep; const char* b3 = b2 + kstep;
;             PG8_LDB(B0, 0, 0); PG8_LDB(B1, 0, 1); PG8_SCHED; PG8_LDA(At, 0, 0); PG8_STAGE(PG8_SA(1, 1), a1 + hstepA, voffA);
;             PG8_WAIT_V(8); PG8_WAIT_L(0); PG8_BAR; PG8_MMA(0, 0, At, B0); PG8_MMA(0, 1, At, B1); PG8_BAR; PG8_SCHED;
;             if (!hf) PG8_LDA(At, 0, 1); PG8_STAGE(PG8_SB(0, 0), b2, voffB); PG8_STAGE(PG8_SB(0, 1), b2 + hstepB, voffB); PG8_STAGE(PG8_SA(0, 0), a2, voffA);
;             PG8_WAIT_V(8); PG8_WAIT_L(0); PG8_BAR; if (!hf) { PG8_MMA(1, 0, At, B0); PG8_MMA(1, 1, At, B1); } PG8_BAR; PG8_SCHED;
.LBB0_1675:
	ds_read_b128 v[142:145], v162
	ds_read_b128 v[146:149], v162 offset:1024
	ds_read_b128 v[150:153], v162 offset:2048
	ds_read_b128 v[154:157], v162 offset:3072
	ds_read_b128 v[166:169], v163
	ds_read_b128 v[170:173], v163 offset:1024
	ds_read_b128 v[174:177], v163 offset:2048
	ds_read_b128 v[178:181], v163 offset:3072
	s_add_i32 s94, s10, 2
	s_add_u32 s60, s58, 0xfff80080
	s_addc_u32 s61, s59, -1
	s_cmp_eq_u32 s91, s10
	s_cselect_b32 s63, s88, s61
	s_cselect_b32 s62, s89, s60
	s_cselect_b32 s61, s43, s93
	s_cselect_b32 s60, s90, s92
	v_lshl_add_u64 v[158:159], s[58:59], 0, v[138:139]
	s_add_i32 m0, s65, 0xc000
	ds_read_b128 v[182:185], v164
	ds_read_b128 v[186:189], v164 offset:1024
	ds_read_b128 v[190:193], v164 offset:2048
	ds_read_b128 v[194:197], v164 offset:3072
	ds_read_b128 v[198:201], v164 offset:4096
	ds_read_b128 v[202:205], v164 offset:5120
	ds_read_b128 v[206:209], v164 offset:6144
	ds_read_b128 v[210:213], v164 offset:7168
	global_load_lds_dwordx4 v[158:159], off
	v_lshl_add_u64 v[158:159], s[58:59], 0, v[140:141]
	s_add_i32 m0, s65, 0xe000
	s_nop 0
	global_load_lds_dwordx4 v[158:159], off
	s_waitcnt vmcnt(8)
	s_waitcnt lgkmcnt(0)
	s_barrier
	s_setprio 1
	s_waitcnt lgkmcnt(0)
	v_mfma_f32_16x16x32_bf16 v[126:129], v[142:145], v[182:185], v[126:129]
	v_mfma_f32_16x16x32_bf16 v[122:125], v[150:153], v[182:185], v[122:125]
	v_mfma_f32_16x16x32_bf16 v[118:121], v[142:145], v[190:193], v[118:121]
	v_mfma_f32_16x16x32_bf16 v[110:113], v[150:153], v[190:193], v[110:113]
	v_mfma_f32_16x16x32_bf16 v[102:105], v[142:145], v[198:201], v[102:105]
	v_mfma_f32_16x16x32_bf16 v[94:97], v[150:153], v[198:201], v[94:97]
	v_mfma_f32_16x16x32_bf16 v[86:89], v[142:145], v[206:209], v[86:89]
	v_mfma_f32_16x16x32_bf16 v[78:81], v[150:153], v[206:209], v[78:81]
	v_mfma_f32_16x16x32_bf16 v[126:129], v[146:149], v[186:189], v[126:129]
	v_mfma_f32_16x16x32_bf16 v[122:125], v[154:157], v[186:189], v[122:125]
	v_mfma_f32_16x16x32_bf16 v[118:121], v[146:149], v[194:197], v[118:121]
	v_mfma_f32_16x16x32_bf16 v[110:113], v[154:157], v[194:197], v[110:113]
	v_mfma_f32_16x16x32_bf16 v[102:105], v[146:149], v[202:205], v[102:105]
	v_mfma_f32_16x16x32_bf16 v[94:97], v[154:157], v[202:205], v[94:97]
	v_mfma_f32_16x16x32_bf16 v[86:89], v[146:149], v[210:213], v[86:89]
	v_mfma_f32_16x16x32_bf16 v[78:81], v[154:157], v[210:213], v[78:81]
	s_setprio 0
	s_setprio 1
	v_mfma_f32_16x16x32_bf16 v[114:117], v[166:169], v[182:185], v[114:117]
	v_mfma_f32_16x16x32_bf16 v[106:109], v[174:177], v[182:185], v[106:109]
	v_mfma_f32_16x16x32_bf16 v[98:101], v[166:169], v[190:193], v[98:101]
	v_mfma_f32_16x16x32_bf16 v[90:93], v[174:177], v[190:193], v[90:93]
	v_mfma_f32_16x16x32_bf16 v[82:85], v[166:169], v[198:201], v[82:85]
	v_mfma_f32_16x16x32_bf16 v[74:77], v[174:177], v[198:201], v[74:77]
	v_mfma_f32_16x16x32_bf16 v[70:73], v[166:169], v[206:209], v[70:73]
	v_mfma_f32_16x16x32_bf16 v[66:69], v[174:177], v[206:209], v[66:69]
	v_mfma_f32_16x16x32_bf16 v[114:117], v[170:173], v[186:189], v[114:117]
	v_mfma_f32_16x16x32_bf16 v[106:109], v[178:181], v[186:189], v[106:109]
	v_mfma_f32_16x16x32_bf16 v[98:101], v[170:173], v[194:197], v[98:101]
	v_mfma_f32_16x16x32_bf16 v[90:93], v[178:181], v[194:197], v[90:93]
	v_mfma_f32_16x16x32_bf16 v[82:85], v[170:173], v[202:205], v[82:85]
	v_mfma_f32_16x16x32_bf16 v[74:77], v[178:181], v[202:205], v[74:77]
	v_mfma_f32_16x16x32_bf16 v[70:73], v[170:173], v[210:213], v[70:73]
	v_mfma_f32_16x16x32_bf16 v[66:69], v[178:181], v[210:213], v[66:69]
	s_setprio 0
	s_barrier
	s_add_i32 s10, s79, s64
	v_lshl_add_u64 v[158:159], s[60:61], 0, v[132:133]
	s_mov_b32 m0, s10
	ds_read_b128 v[182:185], v164 offset:16384
	ds_read_b128 v[186:189], v164 offset:17408
	ds_read_b128 v[190:193], v164 offset:18432
	ds_read_b128 v[194:197], v164 offset:19456
	ds_read_b128 v[198:201], v164 offset:20480
	ds_read_b128 v[202:205], v164 offset:21504
	ds_read_b128 v[206:209], v164 offset:22528
	ds_read_b128 v[210:213], v164 offset:23552
	global_load_lds_dwordx4 v[158:159], off
	s_add_i32 m0, s10, 0x2000
	s_add_u32 s66, s60, 0x20000
	v_lshl_add_u64 v[214:215], s[60:61], 0, v[136:137]
	s_addc_u32 s67, s61, 0
	s_add_i32 s10, s80, s64
	global_load_lds_dwordx4 v[214:215], off
	v_lshl_add_u64 v[216:217], s[66:67], 0, v[132:133]
	s_mov_b32 m0, s10
	v_lshl_add_u64 v[218:219], s[62:63], 0, v[134:135]
	global_load_lds_dwordx4 v[216:217], off
	v_lshl_add_u64 v[216:217], s[66:67], 0, v[136:137]
	s_add_i32 m0, s10, 0x2000
	s_nop 0
	global_load_lds_dwordx4 v[216:217], off
	v_lshl_add_u64 v[216:217], s[62:63], 0, v[130:131]
	s_mov_b32 m0, s65
	s_nop 0
	global_load_lds_dwordx4 v[216:217], off
	s_mov_b32 m0, s70
	s_nop 0
	global_load_lds_dwordx4 v[218:219], off
	s_waitcnt vmcnt(8)
	s_waitcnt lgkmcnt(0)
	s_barrier
; #define PG8_STAGE(bufoff, gbase, voff) do { _Pragma("unroll") for (int _i = 0; _i < 2; ++_i) \
;         __builtin_amdgcn_global_load_lds((const unsigned*)((const char*)(gbase) + (voff)[_i]), (PG8_LAS unsigned*)(lds + (bufoff) + ldsw + _i * 8192), 16, 0, 0); } while (0)
; #define PG8_LDA(dst, b, h) do { _Pragma("unroll") for (int m = 0; m < 4; ++m) frag_load<F8>(dst[m], lds + PG8_SA(b, h) + aoff + m * 2048); } while (0)
; #define PG8_LDB(dst, b, h) do { _Pragma("unroll") for (int n = 0; n < 2; ++n) frag_load<F8>(dst[n], lds + PG8_SB(b, h) + boff + n * 2048); } while (0)
; #define PG8_MMA(ai, bj, At, Bt) do { __builtin_amdgcn_s_setprio(1); _Pragma("unroll") for (int m = 0; m < 4; ++m) _Pragma("unroll") for (int n = 0; n < 2; ++n) frag_mma<F8>(acc[ai][bj][m][n], Bt[n], At[m]); \
;         __builtin_amdgcn_s_setprio(0); } while (0)
; #define PG8_WAIT_V(n) asm volatile("s_waitcnt vmcnt(" #n ")" ::: "memory")
; #define PG8_WAIT_L(n) asm volatile("s_waitcnt lgkmcnt(" #n ")" ::: "memory")
; #define PG8_BAR __builtin_amdgcn_s_barrier()
; #define PG8_SCHED __builtin_amdgcn_sched_barrier(0)
; template <bool F8, class Epi, class Sched>
; __device__ __forceinline__ void gemm_phase(PG8_LAS unsigned char* lds, const Gemm g, const Sched& S, const Epi& E
;     , unsigned long long* stq = nullptr
;     ) {
;     ...
;             PG8_WAIT_V(8); PG8_WAIT_L(0); PG8_BAR; if (!hf) { PG8_MMA(1, 0, At, B0); PG8_MMA(1, 1, At, B1); } PG8_BAR; PG8_SCHED;
;             PG8_LDB(B0, 1, 0); PG8_LDB(B1, 1, 1); PG8_SCHED; PG8_LDA(At, 1, 0); PG8_STAGE(PG8_SA(0, 1), a2 + hstepA, voffA);
;             PG8_WAIT_V(8); PG8_WAIT_L(0); PG8_BAR; PG8_MMA(0, 0, At, B0); PG8_MMA(0, 1, At, B1); PG8_BAR; PG8_SCHED;
	s_setprio 1
	s_waitcnt lgkmcnt(0)
	v_mfma_f32_16x16x32_bf16 v[62:65], v[142:145], v[182:185], v[62:65]
	v_mfma_f32_16x16x32_bf16 v[58:61], v[150:153], v[182:185], v[58:61]
	v_mfma_f32_16x16x32_bf16 v[54:57], v[142:145], v[190:193], v[54:57]
	v_mfma_f32_16x16x32_bf16 v[46:49], v[150:153], v[190:193], v[46:49]
	v_mfma_f32_16x16x32_bf16 v[38:41], v[142:145], v[198:201], v[38:41]
	v_mfma_f32_16x16x32_bf16 v[30:33], v[150:153], v[198:201], v[30:33]
	v_mfma_f32_16x16x32_bf16 v[22:25], v[142:145], v[206:209], v[22:25]
	v_mfma_f32_16x16x32_bf16 v[14:17], v[150:153], v[206:209], v[14:17]
	v_mfma_f32_16x16x32_bf16 v[62:65], v[146:149], v[186:189], v[62:65]
	v_mfma_f32_16x16x32_bf16 v[58:61], v[154:157], v[186:189], v[58:61]
	v_mfma_f32_16x16x32_bf16 v[54:57], v[146:149], v[194:197], v[54:57]
	v_mfma_f32_16x16x32_bf16 v[46:49], v[154:157], v[194:197], v[46:49]
	v_mfma_f32_16x16x32_bf16 v[38:41], v[146:149], v[202:205], v[38:41]
	v_mfma_f32_16x16x32_bf16 v[30:33], v[154:157], v[202:205], v[30:33]
	v_mfma_f32_16x16x32_bf16 v[22:25], v[146:149], v[210:213], v[22:25]
	v_mfma_f32_16x16x32_bf16 v[14:17], v[154:157], v[210:213], v[14:17]
	s_setprio 0
	s_setprio 1
	v_mfma_f32_16x16x32_bf16 v[50:53], v[166:169], v[182:185], v[50:53]
	v_mfma_f32_16x16x32_bf16 v[42:45], v[174:177], v[182:185], v[42:45]
	v_mfma_f32_16x16x32_bf16 v[34:37], v[166:169], v[190:193], v[34:37]
	v_mfma_f32_16x16x32_bf16 v[26:29], v[174:177], v[190:193], v[26:29]
	v_mfma_f32_16x16x32_bf16 v[18:21], v[166:169], v[198:201], v[18:21]
	v_mfma_f32_16x16x32_bf16 v[10:13], v[174:177], v[198:201], v[10:13]
	v_mfma_f32_16x16x32_bf16 v[6:9], v[166:169], v[206:209], v[6:9]
	v_mfma_f32_16x16x32_bf16 v[2:5], v[174:177], v[206:209], v[2:5]
	v_mfma_f32_16x16x32_bf16 v[50:53], v[170:173], v[186:189], v[50:53]
	v_mfma_f32_16x16x32_bf16 v[42:45], v[178:181], v[186:189], v[42:45]
	v_mfma_f32_16x16x32_bf16 v[34:37], v[170:173], v[194:197], v[34:37]
	v_mfma_f32_16x16x32_bf16 v[26:29], v[178:181], v[194:197], v[26:29]
	v_mfma_f32_16x16x32_bf16 v[18:21], v[170:173], v[202:205], v[18:21]
	v_mfma_f32_16x16x32_bf16 v[10:13], v[178:181], v[202:205], v[10:13]
	v_mfma_f32_16x16x32_bf16 v[6:9], v[170:173], v[210:213], v[6:9]
	v_mfma_f32_16x16x32_bf16 v[2:5], v[178:181], v[210:213], v[2:5]
	s_setprio 0
	s_barrier
	s_add_i32 s10, 0, 0x18000
	s_add_i32 s66, 0, 0x1c000
	v_add_u32_e32 v154, s10, v160
	v_add_u32_e32 v165, s66, v160
	ds_read_b128 v[142:145], v154
	ds_read_b128 v[146:149], v154 offset:1024
	ds_read_b128 v[150:153], v154 offset:2048
	ds_read_b128 v[154:157], v154 offset:3072
	ds_read_b128 v[166:169], v165
	ds_read_b128 v[170:173], v165 offset:1024
	ds_read_b128 v[174:177], v165 offset:2048
	ds_read_b128 v[178:181], v165 offset:3072
	s_add_u32 s62, s62, 0x80000
	s_addc_u32 s63, s63, 0
	s_mov_b32 m0, s73
	v_lshl_add_u64 v[222:223], s[62:63], 0, v[130:131]
	ds_read_b128 v[182:185], v164 offset:32768
	ds_read_b128 v[186:189], v164 offset:33792
	ds_read_b128 v[190:193], v164 offset:34816
	ds_read_b128 v[194:197], v164 offset:35840
	ds_read_b128 v[198:201], v164 offset:36864
	ds_read_b128 v[202:205], v164 offset:37888
	ds_read_b128 v[206:209], v164 offset:38912
	ds_read_b128 v[210:213], v164 offset:39936
	global_load_lds_dwordx4 v[222:223], off
	v_lshl_add_u64 v[222:223], s[62:63], 0, v[134:135]
	s_mov_b32 m0, s74
	s_nop 0
	global_load_lds_dwordx4 v[222:223], off
	s_waitcnt vmcnt(8)
	s_waitcnt lgkmcnt(0)
	s_barrier
	s_setprio 1
	s_waitcnt lgkmcnt(0)
	v_mfma_f32_16x16x32_bf16 v[126:129], v[142:145], v[182:185], v[126:129]
	v_mfma_f32_16x16x32_bf16 v[122:125], v[150:153], v[182:185], v[122:125]
	v_mfma_f32_16x16x32_bf16 v[118:121], v[142:145], v[190:193], v[118:121]
	v_mfma_f32_16x16x32_bf16 v[110:113], v[150:153], v[190:193], v[110:113]
	v_mfma_f32_16x16x32_bf16 v[102:105], v[142:145], v[198:201], v[102:105]
	v_mfma_f32_16x16x32_bf16 v[94:97], v[150:153], v[198:201], v[94:97]
	v_mfma_f32_16x16x32_bf16 v[86:89], v[142:145], v[206:209], v[86:89]
	v_mfma_f32_16x16x32_bf16 v[78:81], v[150:153], v[206:209], v[78:81]
	v_mfma_f32_16x16x32_bf16 v[126:129], v[146:149], v[186:189], v[126:129]
	v_mfma_f32_16x16x32_bf16 v[122:125], v[154:157], v[186:189], v[122:125]
	v_mfma_f32_16x16x32_bf16 v[118:121], v[146:149], v[194:197], v[118:121]
	v_mfma_f32_16x16x32_bf16 v[110:113], v[154:157], v[194:197], v[110:113]
	v_mfma_f32_16x16x32_bf16 v[102:105], v[146:149], v[202:205], v[102:105]
	v_mfma_f32_16x16x32_bf16 v[94:97], v[154:157], v[202:205], v[94:97]
	v_mfma_f32_16x16x32_bf16 v[86:89], v[146:149], v[210:213], v[86:89]
	v_mfma_f32_16x16x32_bf16 v[78:81], v[154:157], v[210:213], v[78:81]
	s_setprio 0
	s_setprio 1
	v_mfma_f32_16x16x32_bf16 v[114:117], v[166:169], v[182:185], v[114:117]
	v_mfma_f32_16x16x32_bf16 v[106:109], v[174:177], v[182:185], v[106:109]
	v_mfma_f32_16x16x32_bf16 v[98:101], v[166:169], v[190:193], v[98:101]
	v_mfma_f32_16x16x32_bf16 v[90:93], v[174:177], v[190:193], v[90:93]
	v_mfma_f32_16x16x32_bf16 v[82:85], v[166:169], v[198:201], v[82:85]
	v_mfma_f32_16x16x32_bf16 v[74:77], v[174:177], v[198:201], v[74:77]
	v_mfma_f32_16x16x32_bf16 v[70:73], v[166:169], v[206:209], v[70:73]
	v_mfma_f32_16x16x32_bf16 v[66:69], v[174:177], v[206:209], v[66:69]
	v_mfma_f32_16x16x32_bf16 v[114:117], v[170:173], v[186:189], v[114:117]
	v_mfma_f32_16x16x32_bf16 v[106:109], v[178:181], v[186:189], v[106:109]
	v_mfma_f32_16x16x32_bf16 v[98:101], v[170:173], v[194:197], v[98:101]
	v_mfma_f32_16x16x32_bf16 v[90:93], v[178:181], v[194:197], v[90:93]
	v_mfma_f32_16x16x32_bf16 v[82:85], v[170:173], v[202:205], v[82:85]
	v_mfma_f32_16x16x32_bf16 v[74:77], v[178:181], v[202:205], v[74:77]
	v_mfma_f32_16x16x32_bf16 v[70:73], v[170:173], v[210:213], v[70:73]
	v_mfma_f32_16x16x32_bf16 v[66:69], v[178:181], v[210:213], v[66:69]
	s_setprio 0
	s_barrier
; #define PG8_STAGE(bufoff, gbase, voff) do { _Pragma("unroll") for (int _i = 0; _i < 2; ++_i) \
;         __builtin_amdgcn_global_load_lds((const unsigned*)((const char*)(gbase) + (voff)[_i]), (PG8_LAS unsigned*)(lds + (bufoff) + ldsw + _i * 8192), 16, 0, 0); } while (0)
; #define PG8_LDA(dst, b, h) do { _Pragma("unroll") for (int m = 0; m < 4; ++m) frag_load<F8>(dst[m], lds + PG8_SA(b, h) + aoff + m * 2048); } while (0)
; #define PG8_MMA(ai, bj, At, Bt) do { __builtin_amdgcn_s_setprio(1); _Pragma("unroll") for (int m = 0; m < 4; ++m) _Pragma("unroll") for (int n = 0; n < 2; ++n) frag_mma<F8>(acc[ai][bj][m][n], Bt[n], At[m]); \
;         __builtin_amdgcn_s_setprio(0); } while (0)
; #define PG8_WAIT_V(n) asm volatile("s_waitcnt vmcnt(" #n ")" ::: "memory")
; #define PG8_WAIT_L(n) asm volatile("s_waitcnt lgkmcnt(" #n ")" ::: "memory")
; #define PG8_BAR __builtin_amdgcn_s_barrier()
; #define PG8_SCHED __builtin_amdgcn_sched_barrier(0)
; template <bool F8, class Epi, class Sched>
; __device__ __forceinline__ void gemm_phase(PG8_LAS unsigned char* lds, const Gemm g, const Sched& S, const Epi& E
;     , unsigned long long* stq = nullptr
;     ) {
;     ...
;             if (!hf) PG8_LDA(At, 1, 1); PG8_STAGE(PG8_SB(1, 0), b3, voffB); PG8_STAGE(PG8_SB(1, 1), b3 + hstepB, voffB); PG8_STAGE(PG8_SA(1, 0), a3, voffA);
;             PG8_WAIT_V(8); PG8_WAIT_L(0); PG8_BAR; if (!hf) { PG8_MMA(1, 0, At, B0); PG8_MMA(1, 1, At, B1); } PG8_BAR; PG8_SCHED;
;         }
	s_add_i32 s10, s10, s64
	v_lshl_add_u64 v[158:159], v[158:159], 0, s[18:19]
	s_mov_b32 m0, s10
	ds_read_b128 v[182:185], v164 offset:49152
	ds_read_b128 v[186:189], v164 offset:50176
	ds_read_b128 v[190:193], v164 offset:51200
	ds_read_b128 v[194:197], v164 offset:52224
	ds_read_b128 v[198:201], v164 offset:53248
	ds_read_b128 v[202:205], v164 offset:54272
	ds_read_b128 v[206:209], v164 offset:55296
	ds_read_b128 v[210:213], v164 offset:56320
	global_load_lds_dwordx4 v[158:159], off
	s_add_i32 m0, s10, 0x2000
	s_add_u32 s60, s60, 0x20080
	v_lshl_add_u64 v[158:159], v[214:215], 0, s[18:19]
	s_addc_u32 s61, s61, 0
	s_add_i32 s10, s66, s64
	global_load_lds_dwordx4 v[158:159], off
	v_lshl_add_u64 v[158:159], s[60:61], 0, v[132:133]
	s_mov_b32 m0, s10
	s_nop 0
	global_load_lds_dwordx4 v[158:159], off
	v_lshl_add_u64 v[158:159], s[60:61], 0, v[136:137]
	s_add_i32 m0, s10, 0x2000
	s_nop 0
	global_load_lds_dwordx4 v[158:159], off
	v_lshl_add_u64 v[158:159], v[216:217], 0, s[18:19]
	s_mov_b32 m0, s77
	s_nop 0
	global_load_lds_dwordx4 v[158:159], off
	v_lshl_add_u64 v[158:159], v[218:219], 0, s[18:19]
	s_mov_b32 m0, s78
	s_nop 0
	global_load_lds_dwordx4 v[158:159], off
	s_waitcnt vmcnt(8)
	s_waitcnt lgkmcnt(0)
	s_barrier
	s_setprio 1
	s_waitcnt lgkmcnt(0)
	v_mfma_f32_16x16x32_bf16 v[62:65], v[142:145], v[182:185], v[62:65]
	v_mfma_f32_16x16x32_bf16 v[58:61], v[150:153], v[182:185], v[58:61]
	v_mfma_f32_16x16x32_bf16 v[54:57], v[142:145], v[190:193], v[54:57]
	v_mfma_f32_16x16x32_bf16 v[46:49], v[150:153], v[190:193], v[46:49]
	v_mfma_f32_16x16x32_bf16 v[38:41], v[142:145], v[198:201], v[38:41]
	v_mfma_f32_16x16x32_bf16 v[30:33], v[150:153], v[198:201], v[30:33]
	v_mfma_f32_16x16x32_bf16 v[22:25], v[142:145], v[206:209], v[22:25]
	v_mfma_f32_16x16x32_bf16 v[14:17], v[150:153], v[206:209], v[14:17]
	v_mfma_f32_16x16x32_bf16 v[62:65], v[146:149], v[186:189], v[62:65]
	v_mfma_f32_16x16x32_bf16 v[58:61], v[154:157], v[186:189], v[58:61]
	v_mfma_f32_16x16x32_bf16 v[54:57], v[146:149], v[194:197], v[54:57]
	v_mfma_f32_16x16x32_bf16 v[46:49], v[154:157], v[194:197], v[46:49]
	v_mfma_f32_16x16x32_bf16 v[38:41], v[146:149], v[202:205], v[38:41]
	v_mfma_f32_16x16x32_bf16 v[30:33], v[154:157], v[202:205], v[30:33]
	v_mfma_f32_16x16x32_bf16 v[22:25], v[146:149], v[210:213], v[22:25]
	v_mfma_f32_16x16x32_bf16 v[14:17], v[154:157], v[210:213], v[14:17]
	s_setprio 0
	s_setprio 1
	v_mfma_f32_16x16x32_bf16 v[50:53], v[166:169], v[182:185], v[50:53]
	s_add_u32 s58, s58, 0x100
	v_mfma_f32_16x16x32_bf16 v[42:45], v[174:177], v[182:185], v[42:45]
	s_addc_u32 s59, s59, 0
	v_mfma_f32_16x16x32_bf16 v[34:37], v[166:169], v[190:193], v[34:37]
	s_add_u32 s92, s92, 0x100
	v_mfma_f32_16x16x32_bf16 v[26:29], v[174:177], v[190:193], v[26:29]
	s_addc_u32 s93, s93, 0
	v_mfma_f32_16x16x32_bf16 v[18:21], v[166:169], v[198:201], v[18:21]
	s_cmp_ge_i32 s94, s72
	v_mfma_f32_16x16x32_bf16 v[10:13], v[174:177], v[198:201], v[10:13]
	s_mov_b32 s10, s94
	v_mfma_f32_16x16x32_bf16 v[6:9], v[166:169], v[206:209], v[6:9]
	v_mfma_f32_16x16x32_bf16 v[2:5], v[174:177], v[206:209], v[2:5]
	v_mfma_f32_16x16x32_bf16 v[50:53], v[170:173], v[186:189], v[50:53]
	v_mfma_f32_16x16x32_bf16 v[42:45], v[178:181], v[186:189], v[42:45]
	v_mfma_f32_16x16x32_bf16 v[34:37], v[170:173], v[194:197], v[34:37]
	v_mfma_f32_16x16x32_bf16 v[26:29], v[178:181], v[194:197], v[26:29]
	v_mfma_f32_16x16x32_bf16 v[18:21], v[170:173], v[202:205], v[18:21]
	v_mfma_f32_16x16x32_bf16 v[10:13], v[178:181], v[202:205], v[10:13]
	v_mfma_f32_16x16x32_bf16 v[6:9], v[170:173], v[210:213], v[6:9]
	v_mfma_f32_16x16x32_bf16 v[2:5], v[178:181], v[210:213], v[2:5]
	s_setprio 0
	s_barrier
	s_cbranch_scc0 .LBB0_1675
	s_and_b64 vcc, exec, s[20:21]
	s_cbranch_vccz .LBB0_1678
	s_barrier

; #define PG8_STAGE(bufoff, gbase, voff) do { _Pragma("unroll") for (int _i = 0; _i < 2; ++_i) \
;         __builtin_amdgcn_global_load_lds((const unsigned*)((const char*)(gbase) + (voff)[_i]), (PG8_LAS unsigned*)(lds + (bufoff) + ldsw + _i * 8192), 16, 0, 0); } while (0)
; #define PG8_LDA(dst, b, h) do { _Pragma("unroll") for (int m = 0; m < 4; ++m) frag_load<F8>(dst[m], lds + PG8_SA(b, h) + aoff + m * 2048); } while (0)
; #define PG8_LDB(dst, b, h) do { _Pragma("unroll") for (int n = 0; n < 2; ++n) frag_load<F8>(dst[n], lds + PG8_SB(b, h) + boff + n * 2048); } while (0)
; #define PG8_MMA(ai, bj, At, Bt) do { __builtin_amdgcn_s_setprio(1); _Pragma("unroll") for (int m = 0; m < 4; ++m) _Pragma("unroll") for (int n = 0; n < 2; ++n) frag_mma<F8>(acc[ai][bj][m][n], Bt[n], At[m]); \
;         __builtin_amdgcn_s_setprio(0); } while (0)
; #define PG8_WAIT_V(n) asm volatile("s_waitcnt vmcnt(" #n ")" ::: "memory")
; #define PG8_WAIT_L(n) asm volatile("s_waitcnt lgkmcnt(" #n ")" ::: "memory")
; #define PG8_BAR __builtin_amdgcn_s_barrier()
; #define PG8_SCHED __builtin_amdgcn_sched_barrier(0)
; template <bool F8, class Epi, class Sched>
; __device__ __forceinline__ void gemm_phase(PG8_LAS unsigned char* lds, const Gemm g, const Sched& S, const Epi& E
;     , unsigned long long* stq = nullptr
;     ) {
;     ...
;             const char* a1 = cA + (size_t)(t + 1) * kstep;
;             const char* a2 = last ? nA : cA + (size_t)(t + 2) * kstep; const char* b2 = last ? nB : cB + (size_t)(t + 2) * kstep;
;             const char* a3 = a2 + kstep; const char* b3 = b2 + kstep;
;             PG8_LDB(B0, 0, 0); PG8_LDB(B1, 0, 1); PG8_SCHED; PG8_LDA(At, 0, 0); PG8_STAGE(PG8_SA(1, 1), a1 + hstepA, voffA);
;             PG8_WAIT_V(8); PG8_WAIT_L(0); PG8_BAR; PG8_MMA(0, 0, At, B0); PG8_MMA(0, 1, At, B1); PG8_BAR; PG8_SCHED;
;             if (!hf) PG8_LDA(At, 0, 1); PG8_STAGE(PG8_SB(0, 0), b2, voffB); PG8_STAGE(PG8_SB(0, 1), b2 + hstepB, voffB); PG8_STAGE(PG8_SA(0, 0), a2, voffA);
;             PG8_WAIT_V(8); PG8_WAIT_L(0); PG8_BAR; if (!hf) { PG8_MMA(1, 0, At, B0); PG8_MMA(1, 1, At, B1); } PG8_BAR; PG8_SCHED;
.LBB0_2012:
	ds_read_b128 v[18:21], v184
	ds_read_b128 v[22:25], v184 offset:1024
	ds_read_b128 v[26:29], v184 offset:2048
	ds_read_b128 v[30:33], v184 offset:3072
	ds_read_b128 v[2:5], v185
	ds_read_b128 v[6:9], v185 offset:1024
	ds_read_b128 v[10:13], v185 offset:2048
	ds_read_b128 v[14:17], v185 offset:3072
	s_add_i32 s10, s54, 2
	s_add_u32 s55, s52, 0xfff50080
	s_addc_u32 s56, s53, -1
	s_cmp_eq_u32 s86, s54
	s_cselect_b32 s54, s50, s87
	s_cselect_b32 s57, s49, s56
	s_cselect_b32 s56, s48, s55
	s_cselect_b32 s55, s51, s88
	v_lshl_add_u64 v[212:213], s[52:53], 0, v[170:171]
	s_add_i32 m0, s60, 0xc000
	ds_read_b128 v[174:177], v186
	ds_read_b128 v[178:181], v186 offset:1024
	ds_read_b128 v[188:191], v186 offset:2048
	ds_read_b128 v[192:195], v186 offset:3072
	ds_read_b128 v[196:199], v186 offset:4096
	ds_read_b128 v[200:203], v186 offset:5120
	ds_read_b128 v[204:207], v186 offset:6144
	ds_read_b128 v[208:211], v186 offset:7168
	global_load_lds_dwordx4 v[212:213], off
	v_lshl_add_u64 v[212:213], s[52:53], 0, v[172:173]
	s_add_i32 m0, s60, 0xe000
	s_nop 0
	global_load_lds_dwordx4 v[212:213], off
	s_waitcnt vmcnt(8)
	s_waitcnt lgkmcnt(0)
	s_barrier
	s_setprio 1
	s_waitcnt lgkmcnt(0)
	v_mfma_scale_f32_16x16x128_f8f6f4 v[158:161], v[18:25], v[174:181], v[158:161], v187, v187 op_sel_hi:[0,0,0]
	v_mfma_scale_f32_16x16x128_f8f6f4 v[154:157], v[26:33], v[174:181], v[154:157], v187, v187 op_sel_hi:[0,0,0]
	v_mfma_scale_f32_16x16x128_f8f6f4 v[146:149], v[18:25], v[188:195], v[146:149], v187, v187 op_sel_hi:[0,0,0]
	v_mfma_scale_f32_16x16x128_f8f6f4 v[138:141], v[26:33], v[188:195], v[138:141], v187, v187 op_sel_hi:[0,0,0]
	v_mfma_scale_f32_16x16x128_f8f6f4 v[130:133], v[18:25], v[196:203], v[130:133], v187, v187 op_sel_hi:[0,0,0]
	v_mfma_scale_f32_16x16x128_f8f6f4 v[122:125], v[26:33], v[196:203], v[122:125], v187, v187 op_sel_hi:[0,0,0]
	v_mfma_scale_f32_16x16x128_f8f6f4 v[114:117], v[18:25], v[204:211], v[114:117], v187, v187 op_sel_hi:[0,0,0]
	v_mfma_scale_f32_16x16x128_f8f6f4 v[106:109], v[26:33], v[204:211], v[106:109], v187, v187 op_sel_hi:[0,0,0]
	s_setprio 0
	s_setprio 1
	v_mfma_scale_f32_16x16x128_f8f6f4 v[150:153], v[2:9], v[174:181], v[150:153], v187, v187 op_sel_hi:[0,0,0]
	v_mfma_scale_f32_16x16x128_f8f6f4 v[142:145], v[10:17], v[174:181], v[142:145], v187, v187 op_sel_hi:[0,0,0]
	v_mfma_scale_f32_16x16x128_f8f6f4 v[134:137], v[2:9], v[188:195], v[134:137], v187, v187 op_sel_hi:[0,0,0]
	v_mfma_scale_f32_16x16x128_f8f6f4 v[126:129], v[10:17], v[188:195], v[126:129], v187, v187 op_sel_hi:[0,0,0]
	v_mfma_scale_f32_16x16x128_f8f6f4 v[118:121], v[2:9], v[196:203], v[118:121], v187, v187 op_sel_hi:[0,0,0]
	v_mfma_scale_f32_16x16x128_f8f6f4 v[110:113], v[10:17], v[196:203], v[110:113], v187, v187 op_sel_hi:[0,0,0]
	v_mfma_scale_f32_16x16x128_f8f6f4 v[102:105], v[2:9], v[204:211], v[102:105], v187, v187 op_sel_hi:[0,0,0]
	v_mfma_scale_f32_16x16x128_f8f6f4 v[98:101], v[10:17], v[204:211], v[98:101], v187, v187 op_sel_hi:[0,0,0]
	s_setprio 0
	s_barrier
	s_add_i32 s89, s70, s59
	v_lshl_add_u64 v[174:175], s[54:55], 0, v[164:165]
	s_mov_b32 m0, s89
	ds_read_b128 v[188:191], v186 offset:16384
	ds_read_b128 v[192:195], v186 offset:17408
	ds_read_b128 v[196:199], v186 offset:18432
	ds_read_b128 v[200:203], v186 offset:19456
	ds_read_b128 v[204:207], v186 offset:20480
	ds_read_b128 v[208:211], v186 offset:21504
	ds_read_b128 v[212:215], v186 offset:22528
	ds_read_b128 v[216:219], v186 offset:23552
	global_load_lds_dwordx4 v[174:175], off
	s_add_i32 m0, s89, 0x2000
	s_add_u32 s90, s54, 0xb0000
	v_lshl_add_u64 v[176:177], s[54:55], 0, v[168:169]
	s_addc_u32 s91, s55, 0
	s_add_i32 s89, s73, s59
	global_load_lds_dwordx4 v[176:177], off
	v_lshl_add_u64 v[178:179], s[90:91], 0, v[164:165]
	s_mov_b32 m0, s89
	v_lshl_add_u64 v[180:181], s[56:57], 0, v[166:167]
	global_load_lds_dwordx4 v[178:179], off
	v_lshl_add_u64 v[178:179], s[90:91], 0, v[168:169]
	s_add_i32 m0, s89, 0x2000
	s_nop 0
	global_load_lds_dwordx4 v[178:179], off
	v_lshl_add_u64 v[178:179], s[56:57], 0, v[162:163]
	s_mov_b32 m0, s60
	s_nop 0
	global_load_lds_dwordx4 v[178:179], off
	s_mov_b32 m0, s61
	s_nop 0
	global_load_lds_dwordx4 v[180:181], off
	s_waitcnt vmcnt(8)
	s_waitcnt lgkmcnt(0)
	s_barrier
	s_setprio 1
	s_waitcnt lgkmcnt(0)
	v_mfma_scale_f32_16x16x128_f8f6f4 v[94:97], v[18:25], v[188:195], v[94:97], v187, v187 op_sel_hi:[0,0,0]
	v_mfma_scale_f32_16x16x128_f8f6f4 v[90:93], v[26:33], v[188:195], v[90:93], v187, v187 op_sel_hi:[0,0,0]
	v_mfma_scale_f32_16x16x128_f8f6f4 v[82:85], v[18:25], v[196:203], v[82:85], v187, v187 op_sel_hi:[0,0,0]
	v_mfma_scale_f32_16x16x128_f8f6f4 v[74:77], v[26:33], v[196:203], v[74:77], v187, v187 op_sel_hi:[0,0,0]
	v_mfma_scale_f32_16x16x128_f8f6f4 v[66:69], v[18:25], v[204:211], v[66:69], v187, v187 op_sel_hi:[0,0,0]
	v_mfma_scale_f32_16x16x128_f8f6f4 v[58:61], v[26:33], v[204:211], v[58:61], v187, v187 op_sel_hi:[0,0,0]
	v_mfma_scale_f32_16x16x128_f8f6f4 v[50:53], v[18:25], v[212:219], v[50:53], v187, v187 op_sel_hi:[0,0,0]
	v_mfma_scale_f32_16x16x128_f8f6f4 v[42:45], v[26:33], v[212:219], v[42:45], v187, v187 op_sel_hi:[0,0,0]
	s_setprio 0
	s_setprio 1
	v_mfma_scale_f32_16x16x128_f8f6f4 v[86:89], v[2:9], v[188:195], v[86:89], v187, v187 op_sel_hi:[0,0,0]
	v_mfma_scale_f32_16x16x128_f8f6f4 v[78:81], v[10:17], v[188:195], v[78:81], v187, v187 op_sel_hi:[0,0,0]
	v_mfma_scale_f32_16x16x128_f8f6f4 v[70:73], v[2:9], v[196:203], v[70:73], v187, v187 op_sel_hi:[0,0,0]
	v_mfma_scale_f32_16x16x128_f8f6f4 v[62:65], v[10:17], v[196:203], v[62:65], v187, v187 op_sel_hi:[0,0,0]
	v_mfma_scale_f32_16x16x128_f8f6f4 v[54:57], v[2:9], v[204:211], v[54:57], v187, v187 op_sel_hi:[0,0,0]
	v_mfma_scale_f32_16x16x128_f8f6f4 v[46:49], v[10:17], v[204:211], v[46:49], v187, v187 op_sel_hi:[0,0,0]
	v_mfma_scale_f32_16x16x128_f8f6f4 v[38:41], v[2:9], v[212:219], v[38:41], v187, v187 op_sel_hi:[0,0,0]
	v_mfma_scale_f32_16x16x128_f8f6f4 v[34:37], v[10:17], v[212:219], v[34:37], v187, v187 op_sel_hi:[0,0,0]
	s_setprio 0
	s_barrier
; #define PG8_STAGE(bufoff, gbase, voff) do { _Pragma("unroll") for (int _i = 0; _i < 2; ++_i) \
;         __builtin_amdgcn_global_load_lds((const unsigned*)((const char*)(gbase) + (voff)[_i]), (PG8_LAS unsigned*)(lds + (bufoff) + ldsw + _i * 8192), 16, 0, 0); } while (0)
; #define PG8_LDA(dst, b, h) do { _Pragma("unroll") for (int m = 0; m < 4; ++m) frag_load<F8>(dst[m], lds + PG8_SA(b, h) + aoff + m * 2048); } while (0)
; #define PG8_LDB(dst, b, h) do { _Pragma("unroll") for (int n = 0; n < 2; ++n) frag_load<F8>(dst[n], lds + PG8_SB(b, h) + boff + n * 2048); } while (0)
; #define PG8_MMA(ai, bj, At, Bt) do { __builtin_amdgcn_s_setprio(1); _Pragma("unroll") for (int m = 0; m < 4; ++m) _Pragma("unroll") for (int n = 0; n < 2; ++n) frag_mma<F8>(acc[ai][bj][m][n], Bt[n], At[m]); \
;         __builtin_amdgcn_s_setprio(0); } while (0)
; #define PG8_WAIT_V(n) asm volatile("s_waitcnt vmcnt(" #n ")" ::: "memory")
; #define PG8_WAIT_L(n) asm volatile("s_waitcnt lgkmcnt(" #n ")" ::: "memory")
; #define PG8_BAR __builtin_amdgcn_s_barrier()
; #define PG8_SCHED __builtin_amdgcn_sched_barrier(0)
; template <bool F8, class Epi, class Sched>
; __device__ __forceinline__ void gemm_phase(PG8_LAS unsigned char* lds, const Gemm g, const Sched& S, const Epi& E
;     , unsigned long long* stq = nullptr
;     ) {
;     ...
;             PG8_LDB(B0, 1, 0); PG8_LDB(B1, 1, 1); PG8_SCHED; PG8_LDA(At, 1, 0); PG8_STAGE(PG8_SA(0, 1), a2 + hstepA, voffA);
;             PG8_WAIT_V(8); PG8_WAIT_L(0); PG8_BAR; PG8_MMA(0, 0, At, B0); PG8_MMA(0, 1, At, B1); PG8_BAR; PG8_SCHED;
;             if (!hf) PG8_LDA(At, 1, 1); PG8_STAGE(PG8_SB(1, 0), b3, voffB); PG8_STAGE(PG8_SB(1, 1), b3 + hstepB, voffB); PG8_STAGE(PG8_SA(1, 0), a3, voffA);
;             PG8_WAIT_V(8); PG8_WAIT_L(0); PG8_BAR; if (!hf) { PG8_MMA(1, 0, At, B0); PG8_MMA(1, 1, At, B1); } PG8_BAR; PG8_SCHED;
;         }
	s_add_i32 s89, 0, 0x18000
	s_add_i32 s90, 0, 0x1c000
	v_add_u32_e32 v14, s89, v182
	v_add_u32_e32 v30, s90, v182
	ds_read_b128 v[2:5], v14
	ds_read_b128 v[6:9], v14 offset:1024
	ds_read_b128 v[10:13], v14 offset:2048
	ds_read_b128 v[14:17], v14 offset:3072
	ds_read_b128 v[18:21], v30
	ds_read_b128 v[22:25], v30 offset:1024
	ds_read_b128 v[26:29], v30 offset:2048
	ds_read_b128 v[30:33], v30 offset:3072
	s_add_u32 s56, s56, 0xb0000
	s_addc_u32 s57, s57, 0
	s_mov_b32 m0, s62
	v_lshl_add_u64 v[222:223], s[56:57], 0, v[162:163]
	ds_read_b128 v[188:191], v186 offset:32768
	ds_read_b128 v[192:195], v186 offset:33792
	ds_read_b128 v[196:199], v186 offset:34816
	ds_read_b128 v[200:203], v186 offset:35840
	ds_read_b128 v[204:207], v186 offset:36864
	ds_read_b128 v[208:211], v186 offset:37888
	ds_read_b128 v[212:215], v186 offset:38912
	ds_read_b128 v[216:219], v186 offset:39936
	global_load_lds_dwordx4 v[222:223], off
	v_lshl_add_u64 v[222:223], s[56:57], 0, v[166:167]
	s_mov_b32 m0, s63
	s_nop 0
	global_load_lds_dwordx4 v[222:223], off
	s_waitcnt vmcnt(8)
	s_waitcnt lgkmcnt(0)
	s_barrier
	s_setprio 1
	s_waitcnt lgkmcnt(0)
	v_mfma_scale_f32_16x16x128_f8f6f4 v[158:161], v[2:9], v[188:195], v[158:161], v187, v187 op_sel_hi:[0,0,0]
	v_mfma_scale_f32_16x16x128_f8f6f4 v[154:157], v[10:17], v[188:195], v[154:157], v187, v187 op_sel_hi:[0,0,0]
	v_mfma_scale_f32_16x16x128_f8f6f4 v[146:149], v[2:9], v[196:203], v[146:149], v187, v187 op_sel_hi:[0,0,0]
	v_mfma_scale_f32_16x16x128_f8f6f4 v[138:141], v[10:17], v[196:203], v[138:141], v187, v187 op_sel_hi:[0,0,0]
	v_mfma_scale_f32_16x16x128_f8f6f4 v[130:133], v[2:9], v[204:211], v[130:133], v187, v187 op_sel_hi:[0,0,0]
	v_mfma_scale_f32_16x16x128_f8f6f4 v[122:125], v[10:17], v[204:211], v[122:125], v187, v187 op_sel_hi:[0,0,0]
	v_mfma_scale_f32_16x16x128_f8f6f4 v[114:117], v[2:9], v[212:219], v[114:117], v187, v187 op_sel_hi:[0,0,0]
	v_mfma_scale_f32_16x16x128_f8f6f4 v[106:109], v[10:17], v[212:219], v[106:109], v187, v187 op_sel_hi:[0,0,0]
	s_setprio 0
	s_setprio 1
	v_mfma_scale_f32_16x16x128_f8f6f4 v[150:153], v[18:25], v[188:195], v[150:153], v187, v187 op_sel_hi:[0,0,0]
	v_mfma_scale_f32_16x16x128_f8f6f4 v[142:145], v[26:33], v[188:195], v[142:145], v187, v187 op_sel_hi:[0,0,0]
	v_mfma_scale_f32_16x16x128_f8f6f4 v[134:137], v[18:25], v[196:203], v[134:137], v187, v187 op_sel_hi:[0,0,0]
	v_mfma_scale_f32_16x16x128_f8f6f4 v[126:129], v[26:33], v[196:203], v[126:129], v187, v187 op_sel_hi:[0,0,0]
	v_mfma_scale_f32_16x16x128_f8f6f4 v[118:121], v[18:25], v[204:211], v[118:121], v187, v187 op_sel_hi:[0,0,0]
	v_mfma_scale_f32_16x16x128_f8f6f4 v[110:113], v[26:33], v[204:211], v[110:113], v187, v187 op_sel_hi:[0,0,0]
	v_mfma_scale_f32_16x16x128_f8f6f4 v[102:105], v[18:25], v[212:219], v[102:105], v187, v187 op_sel_hi:[0,0,0]
	v_mfma_scale_f32_16x16x128_f8f6f4 v[98:101], v[26:33], v[212:219], v[98:101], v187, v187 op_sel_hi:[0,0,0]
	s_setprio 0
	s_barrier
	s_add_i32 s56, s89, s59
	v_lshl_add_u64 v[174:175], v[174:175], 0, s[22:23]
	s_mov_b32 m0, s56
	ds_read_b128 v[188:191], v186 offset:49152
	ds_read_b128 v[192:195], v186 offset:50176
	ds_read_b128 v[196:199], v186 offset:51200
	ds_read_b128 v[200:203], v186 offset:52224
	ds_read_b128 v[204:207], v186 offset:53248
	ds_read_b128 v[208:211], v186 offset:54272
	ds_read_b128 v[212:215], v186 offset:55296
	ds_read_b128 v[216:219], v186 offset:56320
	global_load_lds_dwordx4 v[174:175], off
	s_add_i32 m0, s56, 0x2000
	s_add_u32 s54, s54, 0xb0080
	v_lshl_add_u64 v[174:175], v[176:177], 0, s[22:23]
	s_addc_u32 s55, s55, 0
	s_add_i32 s56, s90, s59
	global_load_lds_dwordx4 v[174:175], off
	v_lshl_add_u64 v[174:175], s[54:55], 0, v[164:165]
	s_mov_b32 m0, s56
	s_nop 0
	global_load_lds_dwordx4 v[174:175], off
	v_lshl_add_u64 v[174:175], s[54:55], 0, v[168:169]
	s_add_i32 m0, s56, 0x2000
	s_nop 0
	global_load_lds_dwordx4 v[174:175], off
	v_lshl_add_u64 v[174:175], v[178:179], 0, s[22:23]
	s_mov_b32 m0, s66
	s_nop 0
	global_load_lds_dwordx4 v[174:175], off
	v_lshl_add_u64 v[174:175], v[180:181], 0, s[22:23]
	s_mov_b32 m0, s67
	s_nop 0
	global_load_lds_dwordx4 v[174:175], off
	s_waitcnt vmcnt(8)
	s_waitcnt lgkmcnt(0)
	s_barrier
	s_setprio 1
	s_waitcnt lgkmcnt(0)
	v_mfma_scale_f32_16x16x128_f8f6f4 v[94:97], v[2:9], v[188:195], v[94:97], v187, v187 op_sel_hi:[0,0,0]
	v_mfma_scale_f32_16x16x128_f8f6f4 v[90:93], v[10:17], v[188:195], v[90:93], v187, v187 op_sel_hi:[0,0,0]
	v_mfma_scale_f32_16x16x128_f8f6f4 v[82:85], v[2:9], v[196:203], v[82:85], v187, v187 op_sel_hi:[0,0,0]
	v_mfma_scale_f32_16x16x128_f8f6f4 v[74:77], v[10:17], v[196:203], v[74:77], v187, v187 op_sel_hi:[0,0,0]
	v_mfma_scale_f32_16x16x128_f8f6f4 v[66:69], v[2:9], v[204:211], v[66:69], v187, v187 op_sel_hi:[0,0,0]
	v_mfma_scale_f32_16x16x128_f8f6f4 v[58:61], v[10:17], v[204:211], v[58:61], v187, v187 op_sel_hi:[0,0,0]
	v_mfma_scale_f32_16x16x128_f8f6f4 v[50:53], v[2:9], v[212:219], v[50:53], v187, v187 op_sel_hi:[0,0,0]
	v_mfma_scale_f32_16x16x128_f8f6f4 v[42:45], v[10:17], v[212:219], v[42:45], v187, v187 op_sel_hi:[0,0,0]
	s_setprio 0
	s_setprio 1
	v_mfma_scale_f32_16x16x128_f8f6f4 v[86:89], v[18:25], v[188:195], v[86:89], v187, v187 op_sel_hi:[0,0,0]
	s_add_u32 s52, s52, 0x100
	v_mfma_scale_f32_16x16x128_f8f6f4 v[78:81], v[26:33], v[188:195], v[78:81], v187, v187 op_sel_hi:[0,0,0]
	s_addc_u32 s53, s53, 0
	v_mfma_scale_f32_16x16x128_f8f6f4 v[70:73], v[18:25], v[196:203], v[70:73], v187, v187 op_sel_hi:[0,0,0]
	s_add_u32 s87, s87, 0x100
	v_mfma_scale_f32_16x16x128_f8f6f4 v[62:65], v[26:33], v[196:203], v[62:65], v187, v187 op_sel_hi:[0,0,0]
	s_addc_u32 s88, s88, 0
	v_mfma_scale_f32_16x16x128_f8f6f4 v[54:57], v[18:25], v[204:211], v[54:57], v187, v187 op_sel_hi:[0,0,0]
	s_cmp_ge_i32 s10, s72
	v_mfma_scale_f32_16x16x128_f8f6f4 v[46:49], v[26:33], v[204:211], v[46:49], v187, v187 op_sel_hi:[0,0,0]
	s_mov_b32 s54, s10
	v_mfma_scale_f32_16x16x128_f8f6f4 v[38:41], v[18:25], v[212:219], v[38:41], v187, v187 op_sel_hi:[0,0,0]
	v_mfma_scale_f32_16x16x128_f8f6f4 v[34:37], v[26:33], v[212:219], v[34:37], v187, v187 op_sel_hi:[0,0,0]
	s_setprio 0
	s_barrier
	s_cbranch_scc0 .LBB0_2012
	s_and_b64 vcc, exec, s[24:25]
	s_cbranch_vccz .LBB0_2015
	s_barrier
